# panel: P9->P10 and P10->P11 grid barriers replaced by 4-workgroup panel barriers (sc1 write-through payload stores, per-panel counters, buffer_inv after wait)
# speedup vs baseline: 1.0067x; 1.0008x over previous
; __device__ __forceinline__ unsigned cvt_pk_bf16(float lo, float hi) { unsigned r; asm volatile("v_cvt_pk_bf16_f32 %0, %1, %2" : "=v"(r) : "v"(lo), "v"(hi)); return r; }
;     __device__ __forceinline__ void operator()(const f32x4 (&acc)[2][2][4][2], const Unit& u, int wr, int wc, int fr, int fq) const {
;     ...
;             for (int m = 0; m < 4; ++m) { const size_t ro = (size_t)(row0 + ai * HALF + m * 16) * ldc + col0;
; #pragma unroll
;                 for (int bj = 0; bj < 2; ++bj) { const f32x4 v0 = acc[ai][bj][m][0], v1 = acc[ai][bj][m][1];
;                     const u32x4 gw = *(const u32x4*)(G + ro + bj * HALF);
;                     float r[8]; const float a[8] = {v0[0], v0[1], v0[2], v0[3], v1[0], v1[1], v1[2], v1[3]};
; #pragma unroll
;                     for (int i = 0; i < 4; ++i) { const unsigned w = gw[i]; const float g0 = __builtin_bit_cast(float, w << 16), g1 = __builtin_bit_cast(float, w & 0xffff0000u);
;                         if (MODE == 0) { r[2 * i] = a[2 * i] * __builtin_amdgcn_rcpf(1.0f + __builtin_amdgcn_exp2f(-1.4426950408889634f * g0)); r[2 * i + 1] = a[2 * i + 1] * __builtin_amdgcn_rcpf(1.0f + __builtin_amdgcn_exp2f(-1.4426950408889634f * g1)); }
;                         else { r[2 * i] = g0 * a[2 * i] * __builtin_amdgcn_rcpf(1.0f + __builtin_amdgcn_exp2f(-1.4426950408889634f * a[2 * i])); r[2 * i + 1] = g1 * a[2 * i + 1] * __builtin_amdgcn_rcpf(1.0f + __builtin_amdgcn_exp2f(-1.4426950408889634f * a[2 * i + 1])); } }
;                     if (Add) { const u32x4 aw = *(const u32x4*)(Add + ro + bj * HALF);
; #pragma unroll
;                         for (int i = 0; i < 4; ++i) { const unsigned w = aw[i]; r[2 * i] += __builtin_bit_cast(float, w << 16); r[2 * i + 1] += __builtin_bit_cast(float, w & 0xffff0000u); } }
;                     u32x4 w; w.x = cvt_pk_bf16(r[0], r[1]); w.y = cvt_pk_bf16(r[2], r[3]); w.z = cvt_pk_bf16(r[4], r[5]); w.w = cvt_pk_bf16(r[6], r[7]);
;                     *(u32x4*)(O + ro + bj * HALF) = w; } }
.LBB0_818:
	v_readlane_b32 s4, v254, 37
	v_readlane_b32 s5, v254, 38
	v_lshl_or_b32 v131, s38, 8, v158
	v_lshl_add_u32 v130, v152, 10, v131
	v_lshlrev_b32_e32 v130, 1, v130
	s_mov_b32 s100, 0xbfb8aa3b
	s_nop 1
	v_mov_b32_e32 v131, v130
	global_load_dwordx4 v[182:185], v131, s[4:5]
	v_mov_b32_e32 v131, v130
	global_load_dwordx4 v[186:189], v131, s[4:5] offset:256
	v_add_u32_e32 v131, 0x8000, v130
	global_load_dwordx4 v[190:193], v131, s[4:5]
	v_add_u32_e32 v131, 0x8000, v130
	global_load_dwordx4 v[194:197], v131, s[4:5] offset:256
	v_add_u32_e32 v131, 0x10000, v130
	global_load_dwordx4 v[198:201], v131, s[4:5]
	v_add_u32_e32 v131, 0x10000, v130
	global_load_dwordx4 v[202:205], v131, s[4:5] offset:256
	v_add_u32_e32 v131, 0x18000, v130
	global_load_dwordx4 v[206:209], v131, s[4:5]
	v_add_u32_e32 v131, 0x18000, v130
	global_load_dwordx4 v[210:213], v131, s[4:5] offset:256
	v_add_u32_e32 v131, 0x40000, v130
	global_load_dwordx4 v[214:217], v131, s[4:5]
	v_add_u32_e32 v131, 0x40000, v130
	global_load_dwordx4 v[218:221], v131, s[4:5] offset:256
	s_waitcnt vmcnt(9)
	v_pk_mul_f32 v[166:167], v[126:127], s[100:101] op_sel_hi:[1,0]
	v_pk_mul_f32 v[168:169], v[128:129], s[100:101] op_sel_hi:[1,0]
	v_pk_mul_f32 v[170:171], v[122:123], s[100:101] op_sel_hi:[1,0]
	v_pk_mul_f32 v[172:173], v[124:125], s[100:101] op_sel_hi:[1,0]
	v_exp_f32_e32 v166, v166
	v_exp_f32_e32 v167, v167
	v_exp_f32_e32 v168, v168
	v_exp_f32_e32 v169, v169
	v_exp_f32_e32 v170, v170
	v_exp_f32_e32 v171, v171
	v_exp_f32_e32 v172, v172
	v_exp_f32_e32 v173, v173
	v_lshlrev_b32_e32 v174, 16, v182
	v_and_b32_e32 v175, 0xffff0000, v182
	v_lshlrev_b32_e32 v176, 16, v183
	v_and_b32_e32 v177, 0xffff0000, v183
	v_lshlrev_b32_e32 v178, 16, v184
	v_and_b32_e32 v179, 0xffff0000, v184
	v_lshlrev_b32_e32 v180, 16, v185
	v_and_b32_e32 v181, 0xffff0000, v185
	v_pk_add_f32 v[166:167], v[166:167], 1.0 op_sel_hi:[1,0]
	v_pk_add_f32 v[168:169], v[168:169], 1.0 op_sel_hi:[1,0]
	v_pk_add_f32 v[170:171], v[170:171], 1.0 op_sel_hi:[1,0]
	v_pk_add_f32 v[172:173], v[172:173], 1.0 op_sel_hi:[1,0]
	v_rcp_f32_e32 v166, v166
	v_rcp_f32_e32 v167, v167
	v_rcp_f32_e32 v168, v168
	v_rcp_f32_e32 v169, v169
	v_rcp_f32_e32 v170, v170
	v_rcp_f32_e32 v171, v171
	v_rcp_f32_e32 v172, v172
	v_rcp_f32_e32 v173, v173
	v_pk_mul_f32 v[174:175], v[174:175], v[126:127]
	v_pk_mul_f32 v[176:177], v[176:177], v[128:129]
	v_pk_mul_f32 v[178:179], v[178:179], v[122:123]
	v_pk_mul_f32 v[180:181], v[180:181], v[124:125]
	v_pk_mul_f32 v[174:175], v[174:175], v[166:167]
	v_pk_mul_f32 v[176:177], v[176:177], v[168:169]
	v_pk_mul_f32 v[178:179], v[178:179], v[170:171]
	v_pk_mul_f32 v[180:181], v[180:181], v[172:173]
	v_cvt_pk_bf16_f32 v174, v174, v175
	v_cvt_pk_bf16_f32 v175, v176, v177
	v_cvt_pk_bf16_f32 v176, v178, v179
	v_cvt_pk_bf16_f32 v177, v180, v181
	v_mov_b32_e32 v132, v130
	global_store_dwordx4 v132, v[174:177], s[4:5] sc1
	v_add_u32_e32 v131, 0x48000, v130
	global_load_dwordx4 v[182:185], v131, s[4:5]
	s_waitcnt vmcnt(10)
	v_pk_mul_f32 v[166:167], v[118:119], s[100:101] op_sel_hi:[1,0]
	v_pk_mul_f32 v[168:169], v[120:121], s[100:101] op_sel_hi:[1,0]
	v_pk_mul_f32 v[170:171], v[114:115], s[100:101] op_sel_hi:[1,0]
	v_pk_mul_f32 v[172:173], v[116:117], s[100:101] op_sel_hi:[1,0]
	v_exp_f32_e32 v166, v166
	v_exp_f32_e32 v167, v167
	v_exp_f32_e32 v168, v168
	v_exp_f32_e32 v169, v169
	v_exp_f32_e32 v170, v170
	v_exp_f32_e32 v171, v171
	v_exp_f32_e32 v172, v172
	v_exp_f32_e32 v173, v173
	v_lshlrev_b32_e32 v174, 16, v186
	v_and_b32_e32 v175, 0xffff0000, v186
	v_lshlrev_b32_e32 v176, 16, v187
	v_and_b32_e32 v177, 0xffff0000, v187
	v_lshlrev_b32_e32 v178, 16, v188
	v_and_b32_e32 v179, 0xffff0000, v188
	v_lshlrev_b32_e32 v180, 16, v189
	v_and_b32_e32 v181, 0xffff0000, v189
	v_pk_add_f32 v[166:167], v[166:167], 1.0 op_sel_hi:[1,0]
	v_pk_add_f32 v[168:169], v[168:169], 1.0 op_sel_hi:[1,0]
	v_pk_add_f32 v[170:171], v[170:171], 1.0 op_sel_hi:[1,0]
	v_pk_add_f32 v[172:173], v[172:173], 1.0 op_sel_hi:[1,0]
	v_rcp_f32_e32 v166, v166
	v_rcp_f32_e32 v167, v167
	v_rcp_f32_e32 v168, v168
	v_rcp_f32_e32 v169, v169
	v_rcp_f32_e32 v170, v170
	v_rcp_f32_e32 v171, v171
	v_rcp_f32_e32 v172, v172
	v_rcp_f32_e32 v173, v173
	v_pk_mul_f32 v[174:175], v[174:175], v[118:119]
	v_pk_mul_f32 v[176:177], v[176:177], v[120:121]
	v_pk_mul_f32 v[178:179], v[178:179], v[114:115]
	v_pk_mul_f32 v[180:181], v[180:181], v[116:117]
	v_pk_mul_f32 v[174:175], v[174:175], v[166:167]
	v_pk_mul_f32 v[176:177], v[176:177], v[168:169]
	v_pk_mul_f32 v[178:179], v[178:179], v[170:171]
	v_pk_mul_f32 v[180:181], v[180:181], v[172:173]
	v_cvt_pk_bf16_f32 v174, v174, v175
	v_cvt_pk_bf16_f32 v175, v176, v177
	v_cvt_pk_bf16_f32 v176, v178, v179
	v_cvt_pk_bf16_f32 v177, v180, v181
	v_mov_b32_e32 v132, v130
	global_store_dwordx4 v132, v[174:177], s[4:5] offset:256 sc1
	v_add_u32_e32 v131, 0x48000, v130
	global_load_dwordx4 v[186:189], v131, s[4:5] offset:256
	s_waitcnt vmcnt(11)
; __device__ __forceinline__ unsigned cvt_pk_bf16(float lo, float hi) { unsigned r; asm volatile("v_cvt_pk_bf16_f32 %0, %1, %2" : "=v"(r) : "v"(lo), "v"(hi)); return r; }
;     __device__ __forceinline__ void operator()(const f32x4 (&acc)[2][2][4][2], const Unit& u, int wr, int wc, int fr, int fq) const {
;     ...
;             for (int m = 0; m < 4; ++m) { const size_t ro = (size_t)(row0 + ai * HALF + m * 16) * ldc + col0;
; #pragma unroll
;                 for (int bj = 0; bj < 2; ++bj) { const f32x4 v0 = acc[ai][bj][m][0], v1 = acc[ai][bj][m][1];
;                     const u32x4 gw = *(const u32x4*)(G + ro + bj * HALF);
;                     float r[8]; const float a[8] = {v0[0], v0[1], v0[2], v0[3], v1[0], v1[1], v1[2], v1[3]};
; #pragma unroll
;                     for (int i = 0; i < 4; ++i) { const unsigned w = gw[i]; const float g0 = __builtin_bit_cast(float, w << 16), g1 = __builtin_bit_cast(float, w & 0xffff0000u);
;                         if (MODE == 0) { r[2 * i] = a[2 * i] * __builtin_amdgcn_rcpf(1.0f + __builtin_amdgcn_exp2f(-1.4426950408889634f * g0)); r[2 * i + 1] = a[2 * i + 1] * __builtin_amdgcn_rcpf(1.0f + __builtin_amdgcn_exp2f(-1.4426950408889634f * g1)); }
;                         else { r[2 * i] = g0 * a[2 * i] * __builtin_amdgcn_rcpf(1.0f + __builtin_amdgcn_exp2f(-1.4426950408889634f * a[2 * i])); r[2 * i + 1] = g1 * a[2 * i + 1] * __builtin_amdgcn_rcpf(1.0f + __builtin_amdgcn_exp2f(-1.4426950408889634f * a[2 * i + 1])); } }
;                     if (Add) { const u32x4 aw = *(const u32x4*)(Add + ro + bj * HALF);
; #pragma unroll
;                         for (int i = 0; i < 4; ++i) { const unsigned w = aw[i]; r[2 * i] += __builtin_bit_cast(float, w << 16); r[2 * i + 1] += __builtin_bit_cast(float, w & 0xffff0000u); } }
;                     u32x4 w; w.x = cvt_pk_bf16(r[0], r[1]); w.y = cvt_pk_bf16(r[2], r[3]); w.z = cvt_pk_bf16(r[4], r[5]); w.w = cvt_pk_bf16(r[6], r[7]);
;                     *(u32x4*)(O + ro + bj * HALF) = w; } }
	v_pk_mul_f32 v[166:167], v[110:111], s[100:101] op_sel_hi:[1,0]
	v_pk_mul_f32 v[168:169], v[112:113], s[100:101] op_sel_hi:[1,0]
	v_pk_mul_f32 v[170:171], v[106:107], s[100:101] op_sel_hi:[1,0]
	v_pk_mul_f32 v[172:173], v[108:109], s[100:101] op_sel_hi:[1,0]
	v_exp_f32_e32 v166, v166
	v_exp_f32_e32 v167, v167
	v_exp_f32_e32 v168, v168
	v_exp_f32_e32 v169, v169
	v_exp_f32_e32 v170, v170
	v_exp_f32_e32 v171, v171
	v_exp_f32_e32 v172, v172
	v_exp_f32_e32 v173, v173
	v_lshlrev_b32_e32 v174, 16, v190
	v_and_b32_e32 v175, 0xffff0000, v190
	v_lshlrev_b32_e32 v176, 16, v191
	v_and_b32_e32 v177, 0xffff0000, v191
	v_lshlrev_b32_e32 v178, 16, v192
	v_and_b32_e32 v179, 0xffff0000, v192
	v_lshlrev_b32_e32 v180, 16, v193
	v_and_b32_e32 v181, 0xffff0000, v193
	v_pk_add_f32 v[166:167], v[166:167], 1.0 op_sel_hi:[1,0]
	v_pk_add_f32 v[168:169], v[168:169], 1.0 op_sel_hi:[1,0]
	v_pk_add_f32 v[170:171], v[170:171], 1.0 op_sel_hi:[1,0]
	v_pk_add_f32 v[172:173], v[172:173], 1.0 op_sel_hi:[1,0]
	v_rcp_f32_e32 v166, v166
	v_rcp_f32_e32 v167, v167
	v_rcp_f32_e32 v168, v168
	v_rcp_f32_e32 v169, v169
	v_rcp_f32_e32 v170, v170
	v_rcp_f32_e32 v171, v171
	v_rcp_f32_e32 v172, v172
	v_rcp_f32_e32 v173, v173
	v_pk_mul_f32 v[174:175], v[174:175], v[110:111]
	v_pk_mul_f32 v[176:177], v[176:177], v[112:113]
	v_pk_mul_f32 v[178:179], v[178:179], v[106:107]
	v_pk_mul_f32 v[180:181], v[180:181], v[108:109]
	v_pk_mul_f32 v[174:175], v[174:175], v[166:167]
	v_pk_mul_f32 v[176:177], v[176:177], v[168:169]
	v_pk_mul_f32 v[178:179], v[178:179], v[170:171]
	v_pk_mul_f32 v[180:181], v[180:181], v[172:173]
	v_cvt_pk_bf16_f32 v174, v174, v175
	v_cvt_pk_bf16_f32 v175, v176, v177
	v_cvt_pk_bf16_f32 v176, v178, v179
	v_cvt_pk_bf16_f32 v177, v180, v181
	v_add_u32_e32 v132, 0x8000, v130
	global_store_dwordx4 v132, v[174:177], s[4:5] sc1
	v_add_u32_e32 v131, 0x50000, v130
	global_load_dwordx4 v[190:193], v131, s[4:5]
	s_waitcnt vmcnt(12)
	v_pk_mul_f32 v[166:167], v[102:103], s[100:101] op_sel_hi:[1,0]
	v_pk_mul_f32 v[168:169], v[104:105], s[100:101] op_sel_hi:[1,0]
	v_pk_mul_f32 v[170:171], v[98:99], s[100:101] op_sel_hi:[1,0]
	v_pk_mul_f32 v[172:173], v[100:101], s[100:101] op_sel_hi:[1,0]
	v_exp_f32_e32 v166, v166
	v_exp_f32_e32 v167, v167
	v_exp_f32_e32 v168, v168
	v_exp_f32_e32 v169, v169
	v_exp_f32_e32 v170, v170
	v_exp_f32_e32 v171, v171
	v_exp_f32_e32 v172, v172
	v_exp_f32_e32 v173, v173
	v_lshlrev_b32_e32 v174, 16, v194
	v_and_b32_e32 v175, 0xffff0000, v194
	v_lshlrev_b32_e32 v176, 16, v195
	v_and_b32_e32 v177, 0xffff0000, v195
	v_lshlrev_b32_e32 v178, 16, v196
	v_and_b32_e32 v179, 0xffff0000, v196
	v_lshlrev_b32_e32 v180, 16, v197
	v_and_b32_e32 v181, 0xffff0000, v197
	v_pk_add_f32 v[166:167], v[166:167], 1.0 op_sel_hi:[1,0]
	v_pk_add_f32 v[168:169], v[168:169], 1.0 op_sel_hi:[1,0]
	v_pk_add_f32 v[170:171], v[170:171], 1.0 op_sel_hi:[1,0]
	v_pk_add_f32 v[172:173], v[172:173], 1.0 op_sel_hi:[1,0]
	v_rcp_f32_e32 v166, v166
	v_rcp_f32_e32 v167, v167
	v_rcp_f32_e32 v168, v168
	v_rcp_f32_e32 v169, v169
	v_rcp_f32_e32 v170, v170
	v_rcp_f32_e32 v171, v171
	v_rcp_f32_e32 v172, v172
	v_rcp_f32_e32 v173, v173
	v_pk_mul_f32 v[174:175], v[174:175], v[102:103]
	v_pk_mul_f32 v[176:177], v[176:177], v[104:105]
	v_pk_mul_f32 v[178:179], v[178:179], v[98:99]
	v_pk_mul_f32 v[180:181], v[180:181], v[100:101]
	v_pk_mul_f32 v[174:175], v[174:175], v[166:167]
	v_pk_mul_f32 v[176:177], v[176:177], v[168:169]
	v_pk_mul_f32 v[178:179], v[178:179], v[170:171]
	v_pk_mul_f32 v[180:181], v[180:181], v[172:173]
	v_cvt_pk_bf16_f32 v174, v174, v175
	v_cvt_pk_bf16_f32 v175, v176, v177
	v_cvt_pk_bf16_f32 v176, v178, v179
	v_cvt_pk_bf16_f32 v177, v180, v181
	v_add_u32_e32 v132, 0x8000, v130
	global_store_dwordx4 v132, v[174:177], s[4:5] offset:256 sc1
	v_add_u32_e32 v131, 0x50000, v130
	global_load_dwordx4 v[194:197], v131, s[4:5] offset:256
	s_waitcnt vmcnt(13)
	v_pk_mul_f32 v[166:167], v[94:95], s[100:101] op_sel_hi:[1,0]
	v_pk_mul_f32 v[168:169], v[96:97], s[100:101] op_sel_hi:[1,0]
	v_pk_mul_f32 v[170:171], v[90:91], s[100:101] op_sel_hi:[1,0]
	v_pk_mul_f32 v[172:173], v[92:93], s[100:101] op_sel_hi:[1,0]
	v_exp_f32_e32 v166, v166
	v_exp_f32_e32 v167, v167
	v_exp_f32_e32 v168, v168
	v_exp_f32_e32 v169, v169
	v_exp_f32_e32 v170, v170
	v_exp_f32_e32 v171, v171
	v_exp_f32_e32 v172, v172
	v_exp_f32_e32 v173, v173
	v_lshlrev_b32_e32 v174, 16, v198
	v_and_b32_e32 v175, 0xffff0000, v198
	v_lshlrev_b32_e32 v176, 16, v199
	v_and_b32_e32 v177, 0xffff0000, v199
	v_lshlrev_b32_e32 v178, 16, v200
	v_and_b32_e32 v179, 0xffff0000, v200
	v_lshlrev_b32_e32 v180, 16, v201
	v_and_b32_e32 v181, 0xffff0000, v201
	v_pk_add_f32 v[166:167], v[166:167], 1.0 op_sel_hi:[1,0]
	v_pk_add_f32 v[168:169], v[168:169], 1.0 op_sel_hi:[1,0]
	v_pk_add_f32 v[170:171], v[170:171], 1.0 op_sel_hi:[1,0]
	v_pk_add_f32 v[172:173], v[172:173], 1.0 op_sel_hi:[1,0]
	v_rcp_f32_e32 v166, v166
	v_rcp_f32_e32 v167, v167
	v_rcp_f32_e32 v168, v168
	v_rcp_f32_e32 v169, v169
	v_rcp_f32_e32 v170, v170
	v_rcp_f32_e32 v171, v171
	v_rcp_f32_e32 v172, v172
	v_rcp_f32_e32 v173, v173
	v_pk_mul_f32 v[174:175], v[174:175], v[94:95]
	v_pk_mul_f32 v[176:177], v[176:177], v[96:97]
	v_pk_mul_f32 v[178:179], v[178:179], v[90:91]
	v_pk_mul_f32 v[180:181], v[180:181], v[92:93]
	v_pk_mul_f32 v[174:175], v[174:175], v[166:167]
	v_pk_mul_f32 v[176:177], v[176:177], v[168:169]
	v_pk_mul_f32 v[178:179], v[178:179], v[170:171]
	v_pk_mul_f32 v[180:181], v[180:181], v[172:173]
	v_cvt_pk_bf16_f32 v174, v174, v175
	v_cvt_pk_bf16_f32 v175, v176, v177
	v_cvt_pk_bf16_f32 v176, v178, v179
	v_cvt_pk_bf16_f32 v177, v180, v181
	v_add_u32_e32 v132, 0x10000, v130
	global_store_dwordx4 v132, v[174:177], s[4:5] sc1
	v_add_u32_e32 v131, 0x58000, v130
	global_load_dwordx4 v[198:201], v131, s[4:5]
	s_waitcnt vmcnt(14)
; __device__ __forceinline__ unsigned cvt_pk_bf16(float lo, float hi) { unsigned r; asm volatile("v_cvt_pk_bf16_f32 %0, %1, %2" : "=v"(r) : "v"(lo), "v"(hi)); return r; }
;     __device__ __forceinline__ void operator()(const f32x4 (&acc)[2][2][4][2], const Unit& u, int wr, int wc, int fr, int fq) const {
;     ...
;             for (int m = 0; m < 4; ++m) { const size_t ro = (size_t)(row0 + ai * HALF + m * 16) * ldc + col0;
; #pragma unroll
;                 for (int bj = 0; bj < 2; ++bj) { const f32x4 v0 = acc[ai][bj][m][0], v1 = acc[ai][bj][m][1];
;                     const u32x4 gw = *(const u32x4*)(G + ro + bj * HALF);
;                     float r[8]; const float a[8] = {v0[0], v0[1], v0[2], v0[3], v1[0], v1[1], v1[2], v1[3]};
; #pragma unroll
;                     for (int i = 0; i < 4; ++i) { const unsigned w = gw[i]; const float g0 = __builtin_bit_cast(float, w << 16), g1 = __builtin_bit_cast(float, w & 0xffff0000u);
;                         if (MODE == 0) { r[2 * i] = a[2 * i] * __builtin_amdgcn_rcpf(1.0f + __builtin_amdgcn_exp2f(-1.4426950408889634f * g0)); r[2 * i + 1] = a[2 * i + 1] * __builtin_amdgcn_rcpf(1.0f + __builtin_amdgcn_exp2f(-1.4426950408889634f * g1)); }
;                         else { r[2 * i] = g0 * a[2 * i] * __builtin_amdgcn_rcpf(1.0f + __builtin_amdgcn_exp2f(-1.4426950408889634f * a[2 * i])); r[2 * i + 1] = g1 * a[2 * i + 1] * __builtin_amdgcn_rcpf(1.0f + __builtin_amdgcn_exp2f(-1.4426950408889634f * a[2 * i + 1])); } }
;                     if (Add) { const u32x4 aw = *(const u32x4*)(Add + ro + bj * HALF);
; #pragma unroll
;                         for (int i = 0; i < 4; ++i) { const unsigned w = aw[i]; r[2 * i] += __builtin_bit_cast(float, w << 16); r[2 * i + 1] += __builtin_bit_cast(float, w & 0xffff0000u); } }
;                     u32x4 w; w.x = cvt_pk_bf16(r[0], r[1]); w.y = cvt_pk_bf16(r[2], r[3]); w.z = cvt_pk_bf16(r[4], r[5]); w.w = cvt_pk_bf16(r[6], r[7]);
;                     *(u32x4*)(O + ro + bj * HALF) = w; } }
	v_pk_mul_f32 v[166:167], v[86:87], s[100:101] op_sel_hi:[1,0]
	v_pk_mul_f32 v[168:169], v[88:89], s[100:101] op_sel_hi:[1,0]
	v_pk_mul_f32 v[170:171], v[82:83], s[100:101] op_sel_hi:[1,0]
	v_pk_mul_f32 v[172:173], v[84:85], s[100:101] op_sel_hi:[1,0]
	v_exp_f32_e32 v166, v166
	v_exp_f32_e32 v167, v167
	v_exp_f32_e32 v168, v168
	v_exp_f32_e32 v169, v169
	v_exp_f32_e32 v170, v170
	v_exp_f32_e32 v171, v171
	v_exp_f32_e32 v172, v172
	v_exp_f32_e32 v173, v173
	v_lshlrev_b32_e32 v174, 16, v202
	v_and_b32_e32 v175, 0xffff0000, v202
	v_lshlrev_b32_e32 v176, 16, v203
	v_and_b32_e32 v177, 0xffff0000, v203
	v_lshlrev_b32_e32 v178, 16, v204
	v_and_b32_e32 v179, 0xffff0000, v204
	v_lshlrev_b32_e32 v180, 16, v205
	v_and_b32_e32 v181, 0xffff0000, v205
	v_pk_add_f32 v[166:167], v[166:167], 1.0 op_sel_hi:[1,0]
	v_pk_add_f32 v[168:169], v[168:169], 1.0 op_sel_hi:[1,0]
	v_pk_add_f32 v[170:171], v[170:171], 1.0 op_sel_hi:[1,0]
	v_pk_add_f32 v[172:173], v[172:173], 1.0 op_sel_hi:[1,0]
	v_rcp_f32_e32 v166, v166
	v_rcp_f32_e32 v167, v167
	v_rcp_f32_e32 v168, v168
	v_rcp_f32_e32 v169, v169
	v_rcp_f32_e32 v170, v170
	v_rcp_f32_e32 v171, v171
	v_rcp_f32_e32 v172, v172
	v_rcp_f32_e32 v173, v173
	v_pk_mul_f32 v[174:175], v[174:175], v[86:87]
	v_pk_mul_f32 v[176:177], v[176:177], v[88:89]
	v_pk_mul_f32 v[178:179], v[178:179], v[82:83]
	v_pk_mul_f32 v[180:181], v[180:181], v[84:85]
	v_pk_mul_f32 v[174:175], v[174:175], v[166:167]
	v_pk_mul_f32 v[176:177], v[176:177], v[168:169]
	v_pk_mul_f32 v[178:179], v[178:179], v[170:171]
	v_pk_mul_f32 v[180:181], v[180:181], v[172:173]
	v_cvt_pk_bf16_f32 v174, v174, v175
	v_cvt_pk_bf16_f32 v175, v176, v177
	v_cvt_pk_bf16_f32 v176, v178, v179
	v_cvt_pk_bf16_f32 v177, v180, v181
	v_add_u32_e32 v132, 0x10000, v130
	global_store_dwordx4 v132, v[174:177], s[4:5] offset:256 sc1
	v_add_u32_e32 v131, 0x58000, v130
	global_load_dwordx4 v[202:205], v131, s[4:5] offset:256
	s_waitcnt vmcnt(15)
	v_pk_mul_f32 v[166:167], v[78:79], s[100:101] op_sel_hi:[1,0]
	v_pk_mul_f32 v[168:169], v[80:81], s[100:101] op_sel_hi:[1,0]
	v_pk_mul_f32 v[170:171], v[74:75], s[100:101] op_sel_hi:[1,0]
	v_pk_mul_f32 v[172:173], v[76:77], s[100:101] op_sel_hi:[1,0]
	v_exp_f32_e32 v166, v166
	v_exp_f32_e32 v167, v167
	v_exp_f32_e32 v168, v168
	v_exp_f32_e32 v169, v169
	v_exp_f32_e32 v170, v170
	v_exp_f32_e32 v171, v171
	v_exp_f32_e32 v172, v172
	v_exp_f32_e32 v173, v173
	v_lshlrev_b32_e32 v174, 16, v206
	v_and_b32_e32 v175, 0xffff0000, v206
	v_lshlrev_b32_e32 v176, 16, v207
	v_and_b32_e32 v177, 0xffff0000, v207
	v_lshlrev_b32_e32 v178, 16, v208
	v_and_b32_e32 v179, 0xffff0000, v208
	v_lshlrev_b32_e32 v180, 16, v209
	v_and_b32_e32 v181, 0xffff0000, v209
	v_pk_add_f32 v[166:167], v[166:167], 1.0 op_sel_hi:[1,0]
	v_pk_add_f32 v[168:169], v[168:169], 1.0 op_sel_hi:[1,0]
	v_pk_add_f32 v[170:171], v[170:171], 1.0 op_sel_hi:[1,0]
	v_pk_add_f32 v[172:173], v[172:173], 1.0 op_sel_hi:[1,0]
	v_rcp_f32_e32 v166, v166
	v_rcp_f32_e32 v167, v167
	v_rcp_f32_e32 v168, v168
	v_rcp_f32_e32 v169, v169
	v_rcp_f32_e32 v170, v170
	v_rcp_f32_e32 v171, v171
	v_rcp_f32_e32 v172, v172
	v_rcp_f32_e32 v173, v173
	v_pk_mul_f32 v[174:175], v[174:175], v[78:79]
	v_pk_mul_f32 v[176:177], v[176:177], v[80:81]
	v_pk_mul_f32 v[178:179], v[178:179], v[74:75]
	v_pk_mul_f32 v[180:181], v[180:181], v[76:77]
	v_pk_mul_f32 v[174:175], v[174:175], v[166:167]
	v_pk_mul_f32 v[176:177], v[176:177], v[168:169]
	v_pk_mul_f32 v[178:179], v[178:179], v[170:171]
	v_pk_mul_f32 v[180:181], v[180:181], v[172:173]
	v_cvt_pk_bf16_f32 v174, v174, v175
	v_cvt_pk_bf16_f32 v175, v176, v177
	v_cvt_pk_bf16_f32 v176, v178, v179
	v_cvt_pk_bf16_f32 v177, v180, v181
	v_add_u32_e32 v132, 0x18000, v130
	global_store_dwordx4 v132, v[174:177], s[4:5] sc1
	s_waitcnt vmcnt(15)
	v_pk_mul_f32 v[166:167], v[70:71], s[100:101] op_sel_hi:[1,0]
	v_pk_mul_f32 v[168:169], v[72:73], s[100:101] op_sel_hi:[1,0]
	v_pk_mul_f32 v[170:171], v[66:67], s[100:101] op_sel_hi:[1,0]
	v_pk_mul_f32 v[172:173], v[68:69], s[100:101] op_sel_hi:[1,0]
	v_exp_f32_e32 v166, v166
	v_exp_f32_e32 v167, v167
	v_exp_f32_e32 v168, v168
	v_exp_f32_e32 v169, v169
	v_exp_f32_e32 v170, v170
	v_exp_f32_e32 v171, v171
	v_exp_f32_e32 v172, v172
	v_exp_f32_e32 v173, v173
	v_lshlrev_b32_e32 v174, 16, v210
	v_and_b32_e32 v175, 0xffff0000, v210
	v_lshlrev_b32_e32 v176, 16, v211
	v_and_b32_e32 v177, 0xffff0000, v211
	v_lshlrev_b32_e32 v178, 16, v212
	v_and_b32_e32 v179, 0xffff0000, v212
	v_lshlrev_b32_e32 v180, 16, v213
	v_and_b32_e32 v181, 0xffff0000, v213
	v_pk_add_f32 v[166:167], v[166:167], 1.0 op_sel_hi:[1,0]
	v_pk_add_f32 v[168:169], v[168:169], 1.0 op_sel_hi:[1,0]
	v_pk_add_f32 v[170:171], v[170:171], 1.0 op_sel_hi:[1,0]
	v_pk_add_f32 v[172:173], v[172:173], 1.0 op_sel_hi:[1,0]
	v_rcp_f32_e32 v166, v166
	v_rcp_f32_e32 v167, v167
	v_rcp_f32_e32 v168, v168
	v_rcp_f32_e32 v169, v169
	v_rcp_f32_e32 v170, v170
	v_rcp_f32_e32 v171, v171
	v_rcp_f32_e32 v172, v172
	v_rcp_f32_e32 v173, v173
	v_pk_mul_f32 v[174:175], v[174:175], v[70:71]
	v_pk_mul_f32 v[176:177], v[176:177], v[72:73]
	v_pk_mul_f32 v[178:179], v[178:179], v[66:67]
	v_pk_mul_f32 v[180:181], v[180:181], v[68:69]
	v_pk_mul_f32 v[174:175], v[174:175], v[166:167]
	v_pk_mul_f32 v[176:177], v[176:177], v[168:169]
	v_pk_mul_f32 v[178:179], v[178:179], v[170:171]
	v_pk_mul_f32 v[180:181], v[180:181], v[172:173]
	v_cvt_pk_bf16_f32 v174, v174, v175
	v_cvt_pk_bf16_f32 v175, v176, v177
	v_cvt_pk_bf16_f32 v176, v178, v179
	v_cvt_pk_bf16_f32 v177, v180, v181
	v_add_u32_e32 v132, 0x18000, v130
	global_store_dwordx4 v132, v[174:177], s[4:5] offset:256 sc1
	s_waitcnt vmcnt(15)
; __device__ __forceinline__ unsigned cvt_pk_bf16(float lo, float hi) { unsigned r; asm volatile("v_cvt_pk_bf16_f32 %0, %1, %2" : "=v"(r) : "v"(lo), "v"(hi)); return r; }
;     __device__ __forceinline__ void operator()(const f32x4 (&acc)[2][2][4][2], const Unit& u, int wr, int wc, int fr, int fq) const {
;     ...
;             for (int m = 0; m < 4; ++m) { const size_t ro = (size_t)(row0 + ai * HALF + m * 16) * ldc + col0;
; #pragma unroll
;                 for (int bj = 0; bj < 2; ++bj) { const f32x4 v0 = acc[ai][bj][m][0], v1 = acc[ai][bj][m][1];
;                     const u32x4 gw = *(const u32x4*)(G + ro + bj * HALF);
;                     float r[8]; const float a[8] = {v0[0], v0[1], v0[2], v0[3], v1[0], v1[1], v1[2], v1[3]};
; #pragma unroll
;                     for (int i = 0; i < 4; ++i) { const unsigned w = gw[i]; const float g0 = __builtin_bit_cast(float, w << 16), g1 = __builtin_bit_cast(float, w & 0xffff0000u);
;                         if (MODE == 0) { r[2 * i] = a[2 * i] * __builtin_amdgcn_rcpf(1.0f + __builtin_amdgcn_exp2f(-1.4426950408889634f * g0)); r[2 * i + 1] = a[2 * i + 1] * __builtin_amdgcn_rcpf(1.0f + __builtin_amdgcn_exp2f(-1.4426950408889634f * g1)); }
;                         else { r[2 * i] = g0 * a[2 * i] * __builtin_amdgcn_rcpf(1.0f + __builtin_amdgcn_exp2f(-1.4426950408889634f * a[2 * i])); r[2 * i + 1] = g1 * a[2 * i + 1] * __builtin_amdgcn_rcpf(1.0f + __builtin_amdgcn_exp2f(-1.4426950408889634f * a[2 * i + 1])); } }
;                     if (Add) { const u32x4 aw = *(const u32x4*)(Add + ro + bj * HALF);
; #pragma unroll
;                         for (int i = 0; i < 4; ++i) { const unsigned w = aw[i]; r[2 * i] += __builtin_bit_cast(float, w << 16); r[2 * i + 1] += __builtin_bit_cast(float, w & 0xffff0000u); } }
;                     u32x4 w; w.x = cvt_pk_bf16(r[0], r[1]); w.y = cvt_pk_bf16(r[2], r[3]); w.z = cvt_pk_bf16(r[4], r[5]); w.w = cvt_pk_bf16(r[6], r[7]);
;                     *(u32x4*)(O + ro + bj * HALF) = w; } }
	v_pk_mul_f32 v[166:167], v[62:63], s[100:101] op_sel_hi:[1,0]
	v_pk_mul_f32 v[168:169], v[64:65], s[100:101] op_sel_hi:[1,0]
	v_pk_mul_f32 v[170:171], v[58:59], s[100:101] op_sel_hi:[1,0]
	v_pk_mul_f32 v[172:173], v[60:61], s[100:101] op_sel_hi:[1,0]
	v_exp_f32_e32 v166, v166
	v_exp_f32_e32 v167, v167
	v_exp_f32_e32 v168, v168
	v_exp_f32_e32 v169, v169
	v_exp_f32_e32 v170, v170
	v_exp_f32_e32 v171, v171
	v_exp_f32_e32 v172, v172
	v_exp_f32_e32 v173, v173
	v_lshlrev_b32_e32 v174, 16, v214
	v_and_b32_e32 v175, 0xffff0000, v214
	v_lshlrev_b32_e32 v176, 16, v215
	v_and_b32_e32 v177, 0xffff0000, v215
	v_lshlrev_b32_e32 v178, 16, v216
	v_and_b32_e32 v179, 0xffff0000, v216
	v_lshlrev_b32_e32 v180, 16, v217
	v_and_b32_e32 v181, 0xffff0000, v217
	v_pk_add_f32 v[166:167], v[166:167], 1.0 op_sel_hi:[1,0]
	v_pk_add_f32 v[168:169], v[168:169], 1.0 op_sel_hi:[1,0]
	v_pk_add_f32 v[170:171], v[170:171], 1.0 op_sel_hi:[1,0]
	v_pk_add_f32 v[172:173], v[172:173], 1.0 op_sel_hi:[1,0]
	v_rcp_f32_e32 v166, v166
	v_rcp_f32_e32 v167, v167
	v_rcp_f32_e32 v168, v168
	v_rcp_f32_e32 v169, v169
	v_rcp_f32_e32 v170, v170
	v_rcp_f32_e32 v171, v171
	v_rcp_f32_e32 v172, v172
	v_rcp_f32_e32 v173, v173
	v_pk_mul_f32 v[174:175], v[174:175], v[62:63]
	v_pk_mul_f32 v[176:177], v[176:177], v[64:65]
	v_pk_mul_f32 v[178:179], v[178:179], v[58:59]
	v_pk_mul_f32 v[180:181], v[180:181], v[60:61]
	v_pk_mul_f32 v[174:175], v[174:175], v[166:167]
	v_pk_mul_f32 v[176:177], v[176:177], v[168:169]
	v_pk_mul_f32 v[178:179], v[178:179], v[170:171]
	v_pk_mul_f32 v[180:181], v[180:181], v[172:173]
	v_cvt_pk_bf16_f32 v174, v174, v175
	v_cvt_pk_bf16_f32 v175, v176, v177
	v_cvt_pk_bf16_f32 v176, v178, v179
	v_cvt_pk_bf16_f32 v177, v180, v181
	v_add_u32_e32 v132, 0x40000, v130
	global_store_dwordx4 v132, v[174:177], s[4:5] sc1
	s_waitcnt vmcnt(15)
	v_pk_mul_f32 v[166:167], v[54:55], s[100:101] op_sel_hi:[1,0]
	v_pk_mul_f32 v[168:169], v[56:57], s[100:101] op_sel_hi:[1,0]
	v_pk_mul_f32 v[170:171], v[50:51], s[100:101] op_sel_hi:[1,0]
	v_pk_mul_f32 v[172:173], v[52:53], s[100:101] op_sel_hi:[1,0]
	v_exp_f32_e32 v166, v166
	v_exp_f32_e32 v167, v167
	v_exp_f32_e32 v168, v168
	v_exp_f32_e32 v169, v169
	v_exp_f32_e32 v170, v170
	v_exp_f32_e32 v171, v171
	v_exp_f32_e32 v172, v172
	v_exp_f32_e32 v173, v173
	v_lshlrev_b32_e32 v174, 16, v218
	v_and_b32_e32 v175, 0xffff0000, v218
	v_lshlrev_b32_e32 v176, 16, v219
	v_and_b32_e32 v177, 0xffff0000, v219
	v_lshlrev_b32_e32 v178, 16, v220
	v_and_b32_e32 v179, 0xffff0000, v220
	v_lshlrev_b32_e32 v180, 16, v221
	v_and_b32_e32 v181, 0xffff0000, v221
	v_pk_add_f32 v[166:167], v[166:167], 1.0 op_sel_hi:[1,0]
	v_pk_add_f32 v[168:169], v[168:169], 1.0 op_sel_hi:[1,0]
	v_pk_add_f32 v[170:171], v[170:171], 1.0 op_sel_hi:[1,0]
	v_pk_add_f32 v[172:173], v[172:173], 1.0 op_sel_hi:[1,0]
	v_rcp_f32_e32 v166, v166
	v_rcp_f32_e32 v167, v167
	v_rcp_f32_e32 v168, v168
	v_rcp_f32_e32 v169, v169
	v_rcp_f32_e32 v170, v170
	v_rcp_f32_e32 v171, v171
	v_rcp_f32_e32 v172, v172
	v_rcp_f32_e32 v173, v173
	v_pk_mul_f32 v[174:175], v[174:175], v[54:55]
	v_pk_mul_f32 v[176:177], v[176:177], v[56:57]
	v_pk_mul_f32 v[178:179], v[178:179], v[50:51]
	v_pk_mul_f32 v[180:181], v[180:181], v[52:53]
	v_pk_mul_f32 v[174:175], v[174:175], v[166:167]
	v_pk_mul_f32 v[176:177], v[176:177], v[168:169]
	v_pk_mul_f32 v[178:179], v[178:179], v[170:171]
	v_pk_mul_f32 v[180:181], v[180:181], v[172:173]
	v_cvt_pk_bf16_f32 v174, v174, v175
	v_cvt_pk_bf16_f32 v175, v176, v177
	v_cvt_pk_bf16_f32 v176, v178, v179
	v_cvt_pk_bf16_f32 v177, v180, v181
	v_add_u32_e32 v132, 0x40000, v130
	global_store_dwordx4 v132, v[174:177], s[4:5] offset:256 sc1
	s_waitcnt vmcnt(14)
	v_pk_mul_f32 v[166:167], v[46:47], s[100:101] op_sel_hi:[1,0]
	v_pk_mul_f32 v[168:169], v[48:49], s[100:101] op_sel_hi:[1,0]
	v_pk_mul_f32 v[170:171], v[42:43], s[100:101] op_sel_hi:[1,0]
	v_pk_mul_f32 v[172:173], v[44:45], s[100:101] op_sel_hi:[1,0]
	v_exp_f32_e32 v166, v166
	v_exp_f32_e32 v167, v167
	v_exp_f32_e32 v168, v168
	v_exp_f32_e32 v169, v169
	v_exp_f32_e32 v170, v170
	v_exp_f32_e32 v171, v171
	v_exp_f32_e32 v172, v172
	v_exp_f32_e32 v173, v173
	v_lshlrev_b32_e32 v174, 16, v182
	v_and_b32_e32 v175, 0xffff0000, v182
	v_lshlrev_b32_e32 v176, 16, v183
	v_and_b32_e32 v177, 0xffff0000, v183
	v_lshlrev_b32_e32 v178, 16, v184
	v_and_b32_e32 v179, 0xffff0000, v184
	v_lshlrev_b32_e32 v180, 16, v185
	v_and_b32_e32 v181, 0xffff0000, v185
	v_pk_add_f32 v[166:167], v[166:167], 1.0 op_sel_hi:[1,0]
	v_pk_add_f32 v[168:169], v[168:169], 1.0 op_sel_hi:[1,0]
	v_pk_add_f32 v[170:171], v[170:171], 1.0 op_sel_hi:[1,0]
	v_pk_add_f32 v[172:173], v[172:173], 1.0 op_sel_hi:[1,0]
	v_rcp_f32_e32 v166, v166
	v_rcp_f32_e32 v167, v167
	v_rcp_f32_e32 v168, v168
	v_rcp_f32_e32 v169, v169
	v_rcp_f32_e32 v170, v170
	v_rcp_f32_e32 v171, v171
	v_rcp_f32_e32 v172, v172
	v_rcp_f32_e32 v173, v173
	v_pk_mul_f32 v[174:175], v[174:175], v[46:47]
	v_pk_mul_f32 v[176:177], v[176:177], v[48:49]
	v_pk_mul_f32 v[178:179], v[178:179], v[42:43]
	v_pk_mul_f32 v[180:181], v[180:181], v[44:45]
	v_pk_mul_f32 v[174:175], v[174:175], v[166:167]
	v_pk_mul_f32 v[176:177], v[176:177], v[168:169]
	v_pk_mul_f32 v[178:179], v[178:179], v[170:171]
	v_pk_mul_f32 v[180:181], v[180:181], v[172:173]
	v_cvt_pk_bf16_f32 v174, v174, v175
	v_cvt_pk_bf16_f32 v175, v176, v177
	v_cvt_pk_bf16_f32 v176, v178, v179
	v_cvt_pk_bf16_f32 v177, v180, v181
	v_add_u32_e32 v132, 0x48000, v130
	global_store_dwordx4 v132, v[174:177], s[4:5] sc1
	s_waitcnt vmcnt(13)
; __device__ __forceinline__ unsigned cvt_pk_bf16(float lo, float hi) { unsigned r; asm volatile("v_cvt_pk_bf16_f32 %0, %1, %2" : "=v"(r) : "v"(lo), "v"(hi)); return r; }
;     __device__ __forceinline__ void operator()(const f32x4 (&acc)[2][2][4][2], const Unit& u, int wr, int wc, int fr, int fq) const {
;     ...
;             for (int m = 0; m < 4; ++m) { const size_t ro = (size_t)(row0 + ai * HALF + m * 16) * ldc + col0;
; #pragma unroll
;                 for (int bj = 0; bj < 2; ++bj) { const f32x4 v0 = acc[ai][bj][m][0], v1 = acc[ai][bj][m][1];
;                     const u32x4 gw = *(const u32x4*)(G + ro + bj * HALF);
;                     float r[8]; const float a[8] = {v0[0], v0[1], v0[2], v0[3], v1[0], v1[1], v1[2], v1[3]};
; #pragma unroll
;                     for (int i = 0; i < 4; ++i) { const unsigned w = gw[i]; const float g0 = __builtin_bit_cast(float, w << 16), g1 = __builtin_bit_cast(float, w & 0xffff0000u);
;                         if (MODE == 0) { r[2 * i] = a[2 * i] * __builtin_amdgcn_rcpf(1.0f + __builtin_amdgcn_exp2f(-1.4426950408889634f * g0)); r[2 * i + 1] = a[2 * i + 1] * __builtin_amdgcn_rcpf(1.0f + __builtin_amdgcn_exp2f(-1.4426950408889634f * g1)); }
;                         else { r[2 * i] = g0 * a[2 * i] * __builtin_amdgcn_rcpf(1.0f + __builtin_amdgcn_exp2f(-1.4426950408889634f * a[2 * i])); r[2 * i + 1] = g1 * a[2 * i + 1] * __builtin_amdgcn_rcpf(1.0f + __builtin_amdgcn_exp2f(-1.4426950408889634f * a[2 * i + 1])); } }
;                     if (Add) { const u32x4 aw = *(const u32x4*)(Add + ro + bj * HALF);
; #pragma unroll
;                         for (int i = 0; i < 4; ++i) { const unsigned w = aw[i]; r[2 * i] += __builtin_bit_cast(float, w << 16); r[2 * i + 1] += __builtin_bit_cast(float, w & 0xffff0000u); } }
;                     u32x4 w; w.x = cvt_pk_bf16(r[0], r[1]); w.y = cvt_pk_bf16(r[2], r[3]); w.z = cvt_pk_bf16(r[4], r[5]); w.w = cvt_pk_bf16(r[6], r[7]);
;                     *(u32x4*)(O + ro + bj * HALF) = w; } }
	v_pk_mul_f32 v[166:167], v[38:39], s[100:101] op_sel_hi:[1,0]
	v_pk_mul_f32 v[168:169], v[40:41], s[100:101] op_sel_hi:[1,0]
	v_pk_mul_f32 v[170:171], v[34:35], s[100:101] op_sel_hi:[1,0]
	v_pk_mul_f32 v[172:173], v[36:37], s[100:101] op_sel_hi:[1,0]
	v_exp_f32_e32 v166, v166
	v_exp_f32_e32 v167, v167
	v_exp_f32_e32 v168, v168
	v_exp_f32_e32 v169, v169
	v_exp_f32_e32 v170, v170
	v_exp_f32_e32 v171, v171
	v_exp_f32_e32 v172, v172
	v_exp_f32_e32 v173, v173
	v_lshlrev_b32_e32 v174, 16, v186
	v_and_b32_e32 v175, 0xffff0000, v186
	v_lshlrev_b32_e32 v176, 16, v187
	v_and_b32_e32 v177, 0xffff0000, v187
	v_lshlrev_b32_e32 v178, 16, v188
	v_and_b32_e32 v179, 0xffff0000, v188
	v_lshlrev_b32_e32 v180, 16, v189
	v_and_b32_e32 v181, 0xffff0000, v189
	v_pk_add_f32 v[166:167], v[166:167], 1.0 op_sel_hi:[1,0]
	v_pk_add_f32 v[168:169], v[168:169], 1.0 op_sel_hi:[1,0]
	v_pk_add_f32 v[170:171], v[170:171], 1.0 op_sel_hi:[1,0]
	v_pk_add_f32 v[172:173], v[172:173], 1.0 op_sel_hi:[1,0]
	v_rcp_f32_e32 v166, v166
	v_rcp_f32_e32 v167, v167
	v_rcp_f32_e32 v168, v168
	v_rcp_f32_e32 v169, v169
	v_rcp_f32_e32 v170, v170
	v_rcp_f32_e32 v171, v171
	v_rcp_f32_e32 v172, v172
	v_rcp_f32_e32 v173, v173
	v_pk_mul_f32 v[174:175], v[174:175], v[38:39]
	v_pk_mul_f32 v[176:177], v[176:177], v[40:41]
	v_pk_mul_f32 v[178:179], v[178:179], v[34:35]
	v_pk_mul_f32 v[180:181], v[180:181], v[36:37]
	v_pk_mul_f32 v[174:175], v[174:175], v[166:167]
	v_pk_mul_f32 v[176:177], v[176:177], v[168:169]
	v_pk_mul_f32 v[178:179], v[178:179], v[170:171]
	v_pk_mul_f32 v[180:181], v[180:181], v[172:173]
	v_cvt_pk_bf16_f32 v174, v174, v175
	v_cvt_pk_bf16_f32 v175, v176, v177
	v_cvt_pk_bf16_f32 v176, v178, v179
	v_cvt_pk_bf16_f32 v177, v180, v181
	v_add_u32_e32 v132, 0x48000, v130
	global_store_dwordx4 v132, v[174:177], s[4:5] offset:256 sc1
	s_waitcnt vmcnt(12)
	v_pk_mul_f32 v[166:167], v[30:31], s[100:101] op_sel_hi:[1,0]
	v_pk_mul_f32 v[168:169], v[32:33], s[100:101] op_sel_hi:[1,0]
	v_pk_mul_f32 v[170:171], v[26:27], s[100:101] op_sel_hi:[1,0]
	v_pk_mul_f32 v[172:173], v[28:29], s[100:101] op_sel_hi:[1,0]
	v_exp_f32_e32 v166, v166
	v_exp_f32_e32 v167, v167
	v_exp_f32_e32 v168, v168
	v_exp_f32_e32 v169, v169
	v_exp_f32_e32 v170, v170
	v_exp_f32_e32 v171, v171
	v_exp_f32_e32 v172, v172
	v_exp_f32_e32 v173, v173
	v_lshlrev_b32_e32 v174, 16, v190
	v_and_b32_e32 v175, 0xffff0000, v190
	v_lshlrev_b32_e32 v176, 16, v191
	v_and_b32_e32 v177, 0xffff0000, v191
	v_lshlrev_b32_e32 v178, 16, v192
	v_and_b32_e32 v179, 0xffff0000, v192
	v_lshlrev_b32_e32 v180, 16, v193
	v_and_b32_e32 v181, 0xffff0000, v193
	v_pk_add_f32 v[166:167], v[166:167], 1.0 op_sel_hi:[1,0]
	v_pk_add_f32 v[168:169], v[168:169], 1.0 op_sel_hi:[1,0]
	v_pk_add_f32 v[170:171], v[170:171], 1.0 op_sel_hi:[1,0]
	v_pk_add_f32 v[172:173], v[172:173], 1.0 op_sel_hi:[1,0]
	v_rcp_f32_e32 v166, v166
	v_rcp_f32_e32 v167, v167
	v_rcp_f32_e32 v168, v168
	v_rcp_f32_e32 v169, v169
	v_rcp_f32_e32 v170, v170
	v_rcp_f32_e32 v171, v171
	v_rcp_f32_e32 v172, v172
	v_rcp_f32_e32 v173, v173
	v_pk_mul_f32 v[174:175], v[174:175], v[30:31]
	v_pk_mul_f32 v[176:177], v[176:177], v[32:33]
	v_pk_mul_f32 v[178:179], v[178:179], v[26:27]
	v_pk_mul_f32 v[180:181], v[180:181], v[28:29]
	v_pk_mul_f32 v[174:175], v[174:175], v[166:167]
	v_pk_mul_f32 v[176:177], v[176:177], v[168:169]
	v_pk_mul_f32 v[178:179], v[178:179], v[170:171]
	v_pk_mul_f32 v[180:181], v[180:181], v[172:173]
	v_cvt_pk_bf16_f32 v174, v174, v175
	v_cvt_pk_bf16_f32 v175, v176, v177
	v_cvt_pk_bf16_f32 v176, v178, v179
	v_cvt_pk_bf16_f32 v177, v180, v181
	v_add_u32_e32 v132, 0x50000, v130
	global_store_dwordx4 v132, v[174:177], s[4:5] sc1
	s_waitcnt vmcnt(11)
	v_pk_mul_f32 v[166:167], v[22:23], s[100:101] op_sel_hi:[1,0]
	v_pk_mul_f32 v[168:169], v[24:25], s[100:101] op_sel_hi:[1,0]
	v_pk_mul_f32 v[170:171], v[18:19], s[100:101] op_sel_hi:[1,0]
	v_pk_mul_f32 v[172:173], v[20:21], s[100:101] op_sel_hi:[1,0]
	v_exp_f32_e32 v166, v166
	v_exp_f32_e32 v167, v167
	v_exp_f32_e32 v168, v168
	v_exp_f32_e32 v169, v169
	v_exp_f32_e32 v170, v170
	v_exp_f32_e32 v171, v171
	v_exp_f32_e32 v172, v172
	v_exp_f32_e32 v173, v173
	v_lshlrev_b32_e32 v174, 16, v194
	v_and_b32_e32 v175, 0xffff0000, v194
	v_lshlrev_b32_e32 v176, 16, v195
	v_and_b32_e32 v177, 0xffff0000, v195
	v_lshlrev_b32_e32 v178, 16, v196
	v_and_b32_e32 v179, 0xffff0000, v196
	v_lshlrev_b32_e32 v180, 16, v197
	v_and_b32_e32 v181, 0xffff0000, v197
	v_pk_add_f32 v[166:167], v[166:167], 1.0 op_sel_hi:[1,0]
	v_pk_add_f32 v[168:169], v[168:169], 1.0 op_sel_hi:[1,0]
	v_pk_add_f32 v[170:171], v[170:171], 1.0 op_sel_hi:[1,0]
	v_pk_add_f32 v[172:173], v[172:173], 1.0 op_sel_hi:[1,0]
	v_rcp_f32_e32 v166, v166
	v_rcp_f32_e32 v167, v167
	v_rcp_f32_e32 v168, v168
	v_rcp_f32_e32 v169, v169
	v_rcp_f32_e32 v170, v170
	v_rcp_f32_e32 v171, v171
	v_rcp_f32_e32 v172, v172
	v_rcp_f32_e32 v173, v173
	v_pk_mul_f32 v[174:175], v[174:175], v[22:23]
	v_pk_mul_f32 v[176:177], v[176:177], v[24:25]
	v_pk_mul_f32 v[178:179], v[178:179], v[18:19]
	v_pk_mul_f32 v[180:181], v[180:181], v[20:21]
	v_pk_mul_f32 v[174:175], v[174:175], v[166:167]
	v_pk_mul_f32 v[176:177], v[176:177], v[168:169]
	v_pk_mul_f32 v[178:179], v[178:179], v[170:171]
	v_pk_mul_f32 v[180:181], v[180:181], v[172:173]
	v_cvt_pk_bf16_f32 v174, v174, v175
	v_cvt_pk_bf16_f32 v175, v176, v177
	v_cvt_pk_bf16_f32 v176, v178, v179
	v_cvt_pk_bf16_f32 v177, v180, v181
	v_add_u32_e32 v132, 0x50000, v130
	global_store_dwordx4 v132, v[174:177], s[4:5] offset:256 sc1
	s_waitcnt vmcnt(10)
; __device__ __forceinline__ unsigned cvt_pk_bf16(float lo, float hi) { unsigned r; asm volatile("v_cvt_pk_bf16_f32 %0, %1, %2" : "=v"(r) : "v"(lo), "v"(hi)); return r; }
;     __device__ __forceinline__ void operator()(const f32x4 (&acc)[2][2][4][2], const Unit& u, int wr, int wc, int fr, int fq) const {
;     ...
;             for (int m = 0; m < 4; ++m) { const size_t ro = (size_t)(row0 + ai * HALF + m * 16) * ldc + col0;
; #pragma unroll
;                 for (int bj = 0; bj < 2; ++bj) { const f32x4 v0 = acc[ai][bj][m][0], v1 = acc[ai][bj][m][1];
;                     const u32x4 gw = *(const u32x4*)(G + ro + bj * HALF);
;                     float r[8]; const float a[8] = {v0[0], v0[1], v0[2], v0[3], v1[0], v1[1], v1[2], v1[3]};
; #pragma unroll
;                     for (int i = 0; i < 4; ++i) { const unsigned w = gw[i]; const float g0 = __builtin_bit_cast(float, w << 16), g1 = __builtin_bit_cast(float, w & 0xffff0000u);
;                         if (MODE == 0) { r[2 * i] = a[2 * i] * __builtin_amdgcn_rcpf(1.0f + __builtin_amdgcn_exp2f(-1.4426950408889634f * g0)); r[2 * i + 1] = a[2 * i + 1] * __builtin_amdgcn_rcpf(1.0f + __builtin_amdgcn_exp2f(-1.4426950408889634f * g1)); }
;                         else { r[2 * i] = g0 * a[2 * i] * __builtin_amdgcn_rcpf(1.0f + __builtin_amdgcn_exp2f(-1.4426950408889634f * a[2 * i])); r[2 * i + 1] = g1 * a[2 * i + 1] * __builtin_amdgcn_rcpf(1.0f + __builtin_amdgcn_exp2f(-1.4426950408889634f * a[2 * i + 1])); } }
;                     if (Add) { const u32x4 aw = *(const u32x4*)(Add + ro + bj * HALF);
; #pragma unroll
;                         for (int i = 0; i < 4; ++i) { const unsigned w = aw[i]; r[2 * i] += __builtin_bit_cast(float, w << 16); r[2 * i + 1] += __builtin_bit_cast(float, w & 0xffff0000u); } }
;                     u32x4 w; w.x = cvt_pk_bf16(r[0], r[1]); w.y = cvt_pk_bf16(r[2], r[3]); w.z = cvt_pk_bf16(r[4], r[5]); w.w = cvt_pk_bf16(r[6], r[7]);
;                     *(u32x4*)(O + ro + bj * HALF) = w; } }
	v_pk_mul_f32 v[166:167], v[14:15], s[100:101] op_sel_hi:[1,0]
	v_pk_mul_f32 v[168:169], v[16:17], s[100:101] op_sel_hi:[1,0]
	v_pk_mul_f32 v[170:171], v[10:11], s[100:101] op_sel_hi:[1,0]
	v_pk_mul_f32 v[172:173], v[12:13], s[100:101] op_sel_hi:[1,0]
	v_exp_f32_e32 v166, v166
	v_exp_f32_e32 v167, v167
	v_exp_f32_e32 v168, v168
	v_exp_f32_e32 v169, v169
	v_exp_f32_e32 v170, v170
	v_exp_f32_e32 v171, v171
	v_exp_f32_e32 v172, v172
	v_exp_f32_e32 v173, v173
	v_lshlrev_b32_e32 v174, 16, v198
	v_and_b32_e32 v175, 0xffff0000, v198
	v_lshlrev_b32_e32 v176, 16, v199
	v_and_b32_e32 v177, 0xffff0000, v199
	v_lshlrev_b32_e32 v178, 16, v200
	v_and_b32_e32 v179, 0xffff0000, v200
	v_lshlrev_b32_e32 v180, 16, v201
	v_and_b32_e32 v181, 0xffff0000, v201
	v_pk_add_f32 v[166:167], v[166:167], 1.0 op_sel_hi:[1,0]
	v_pk_add_f32 v[168:169], v[168:169], 1.0 op_sel_hi:[1,0]
	v_pk_add_f32 v[170:171], v[170:171], 1.0 op_sel_hi:[1,0]
	v_pk_add_f32 v[172:173], v[172:173], 1.0 op_sel_hi:[1,0]
	v_rcp_f32_e32 v166, v166
	v_rcp_f32_e32 v167, v167
	v_rcp_f32_e32 v168, v168
	v_rcp_f32_e32 v169, v169
	v_rcp_f32_e32 v170, v170
	v_rcp_f32_e32 v171, v171
	v_rcp_f32_e32 v172, v172
	v_rcp_f32_e32 v173, v173
	v_pk_mul_f32 v[174:175], v[174:175], v[14:15]
	v_pk_mul_f32 v[176:177], v[176:177], v[16:17]
	v_pk_mul_f32 v[178:179], v[178:179], v[10:11]
	v_pk_mul_f32 v[180:181], v[180:181], v[12:13]
	v_pk_mul_f32 v[174:175], v[174:175], v[166:167]
	v_pk_mul_f32 v[176:177], v[176:177], v[168:169]
	v_pk_mul_f32 v[178:179], v[178:179], v[170:171]
	v_pk_mul_f32 v[180:181], v[180:181], v[172:173]
	v_cvt_pk_bf16_f32 v174, v174, v175
	v_cvt_pk_bf16_f32 v175, v176, v177
	v_cvt_pk_bf16_f32 v176, v178, v179
	v_cvt_pk_bf16_f32 v177, v180, v181
	v_add_u32_e32 v132, 0x58000, v130
	global_store_dwordx4 v132, v[174:177], s[4:5] sc1
	s_waitcnt vmcnt(9)
	v_pk_mul_f32 v[166:167], v[6:7], s[100:101] op_sel_hi:[1,0]
	v_pk_mul_f32 v[168:169], v[8:9], s[100:101] op_sel_hi:[1,0]
	v_pk_mul_f32 v[170:171], v[2:3], s[100:101] op_sel_hi:[1,0]
	v_pk_mul_f32 v[172:173], v[4:5], s[100:101] op_sel_hi:[1,0]
	v_exp_f32_e32 v166, v166
	v_exp_f32_e32 v167, v167
	v_exp_f32_e32 v168, v168
	v_exp_f32_e32 v169, v169
	v_exp_f32_e32 v170, v170
	v_exp_f32_e32 v171, v171
	v_exp_f32_e32 v172, v172
	v_exp_f32_e32 v173, v173
	v_lshlrev_b32_e32 v174, 16, v202
	v_and_b32_e32 v175, 0xffff0000, v202
	v_lshlrev_b32_e32 v176, 16, v203
	v_and_b32_e32 v177, 0xffff0000, v203
	v_lshlrev_b32_e32 v178, 16, v204
	v_and_b32_e32 v179, 0xffff0000, v204
	v_lshlrev_b32_e32 v180, 16, v205
	v_and_b32_e32 v181, 0xffff0000, v205
	v_pk_add_f32 v[166:167], v[166:167], 1.0 op_sel_hi:[1,0]
	v_pk_add_f32 v[168:169], v[168:169], 1.0 op_sel_hi:[1,0]
	v_pk_add_f32 v[170:171], v[170:171], 1.0 op_sel_hi:[1,0]
	v_pk_add_f32 v[172:173], v[172:173], 1.0 op_sel_hi:[1,0]
	v_rcp_f32_e32 v166, v166
	v_rcp_f32_e32 v167, v167
	v_rcp_f32_e32 v168, v168
	v_rcp_f32_e32 v169, v169
	v_rcp_f32_e32 v170, v170
	v_rcp_f32_e32 v171, v171
	v_rcp_f32_e32 v172, v172
	v_rcp_f32_e32 v173, v173
	v_pk_mul_f32 v[174:175], v[174:175], v[6:7]
	v_pk_mul_f32 v[176:177], v[176:177], v[8:9]
	v_pk_mul_f32 v[178:179], v[178:179], v[2:3]
	v_pk_mul_f32 v[180:181], v[180:181], v[4:5]
	v_pk_mul_f32 v[174:175], v[174:175], v[166:167]
	v_pk_mul_f32 v[176:177], v[176:177], v[168:169]
	v_pk_mul_f32 v[178:179], v[178:179], v[170:171]
	v_pk_mul_f32 v[180:181], v[180:181], v[172:173]
	v_cvt_pk_bf16_f32 v174, v174, v175
	v_cvt_pk_bf16_f32 v175, v176, v177
	v_cvt_pk_bf16_f32 v176, v178, v179
	v_cvt_pk_bf16_f32 v177, v180, v181
	v_add_u32_e32 v132, 0x58000, v130
	global_store_dwordx4 v132, v[174:177], s[4:5] offset:256 sc1
	s_and_b64 vcc, exec, s[2:3]
	s_mov_b64 s[2:3], -1
	s_cbranch_vccnz .LBB0_793

; __device__ __forceinline__ unsigned xb_ld(unsigned* p)              { return __hip_atomic_load(p, __ATOMIC_RELAXED, __HIP_MEMORY_SCOPE_AGENT); }
; __device__ __forceinline__ unsigned xb_add(unsigned* p, unsigned v) { return __hip_atomic_fetch_add(p, v, __ATOMIC_RELAXED, __HIP_MEMORY_SCOPE_AGENT); }
; #define XB_SPIN(cond, bar) do { unsigned _sp = 0; while (cond) { __builtin_amdgcn_s_sleep(1); \
;     if ((++_sp & 255u) == 0u) { if (xb_ld(&(bar)[XB_TMO])) break; if (_sp > XB_SPIN_CAP) { atomicAdd(&(bar)[XB_TMO], 1u); break; } } } } while (0)
; __device__ __forceinline__ void xcd_barrier(const XcdBarrier& b) {
;     asm volatile("s_waitcnt vmcnt(0)" ::: "memory");
;     __syncthreads();
;     if (threadIdx.x == 0) {
;         unsigned* bar = b.bar;
;         __builtin_amdgcn_s_waitcnt(0);
;         unsigned nloc = b.st[0], nx = b.st[1];
;         if (nloc == 0u) { xcd_barrier_complete(bar, b.x, nloc, nx); b.st[0] = nloc; b.st[1] = nx; }
;         const unsigned old = xb_add(&bar[XB_XSUB(b.x)], 1u);
;         const unsigned gen = old / nloc;
;         if (old + 1u == (gen + 1u) * nloc) {
;             __builtin_amdgcn_fence(__ATOMIC_RELEASE, "agent");
;             asm volatile("s_waitcnt vmcnt(0)" ::: "memory");
;             const unsigned og = xb_add(&bar[XB_TOP], 1u);
;             const unsigned tg = og / nx;
;             if (og + 1u == (tg + 1u) * nx) xb_add(&bar[XB_TOPGEN], 1u);
;             else XB_SPIN(xb_ld(&bar[XB_TOPGEN]) == tg, bar);
;             __builtin_amdgcn_fence(__ATOMIC_ACQUIRE, "agent");
;             xb_add(&bar[XB_XGEN(b.x)], 1u);
;             asm volatile("s_waitcnt vmcnt(0)" ::: "memory");
;         } else {
;             XB_SPIN(xb_ld(&bar[XB_XGEN(b.x)]) == gen, bar);
;             __builtin_amdgcn_fence(__ATOMIC_ACQUIRE, "agent");
;             asm volatile("s_waitcnt vmcnt(0)" ::: "memory");
;         }
;     }
;     __syncthreads();
; }
.LBB0_822:
	s_cmp_gt_i32 s87, 10
	s_cselect_b64 s[2:3], -1, 0
	s_and_b64 s[0:1], s[0:1], s[2:3]
	s_andn2_b64 vcc, exec, s[0:1]
	s_cbranch_vccnz .LBB0_876
	s_waitcnt vmcnt(0)
	s_waitcnt vmcnt(0) lgkmcnt(0)
	s_barrier
	s_and_saveexec_b64 s[0:1], s[88:89]
	s_cbranch_execz .LBB0_875
	v_readlane_b32 s4, v250, 6
	v_readlane_b32 s5, v250, 7
	v_readlane_b32 s6, v250, 28
	v_mov_b32_e32 v2, 0
	v_mov_b32_e32 v3, 1
	s_lshr_b32 s6, s6, 3
	s_and_b32 s7, s6, 7
	s_bfe_u32 s6, s6, 0x30003
	s_lshl_b32 s7, s7, 3
	s_add_i32 s6, s6, s7
	s_lshl_b32 s8, s6, 1
	s_and_b32 s8, s8, 63
	s_lshl_b32 s6, s6, 8
	s_lshl_b32 s8, s8, 8
	s_add_u32 s4, s4, 0x4c040
	s_addc_u32 s5, s5, 0
	s_add_u32 s8, s4, s8
	s_addc_u32 s9, s5, 0
	s_add_u32 s4, s4, s6
	s_addc_u32 s5, s5, 0
	s_mov_b32 s7, 0
	global_atomic_add v2, v3, s[4:5]
.Lpb9_poll:
	global_load_dword v4, v2, s[4:5] sc1
	s_add_i32 s7, s7, 1
	s_waitcnt vmcnt(0)
	s_nop 0
	v_readfirstlane_b32 s6, v4
	s_nop 0
	s_nop 0
	s_cmp_ge_u32 s6, 4
	s_cbranch_scc1 .Lpb9_done
	s_cmp_ge_u32 s7, 0x400000
	s_cbranch_scc1 .Lpb9_done
	s_sleep 1
	s_branch .Lpb9_poll
.Lpb9_done:
	buffer_inv sc1
	s_waitcnt vmcnt(0)

; __device__ __forceinline__ unsigned cvt_pk_bf16(float lo, float hi) { unsigned r; asm volatile("v_cvt_pk_bf16_f32 %0, %1, %2" : "=v"(r) : "v"(lo), "v"(hi)); return r; }
;     __device__ __forceinline__ void operator()(const f32x4 (&acc)[2][2][4][2], const Unit& u, int wr, int wc, int fr, int fq) const {
;     ...
;             for (int m = 0; m < 4; ++m) { const size_t ro = (size_t)(row0 + ai * HALF + m * 16) * ldc + col0;
; #pragma unroll
;                 for (int bj = 0; bj < 2; ++bj) { const f32x4 v0 = acc[ai][bj][m][0], v1 = acc[ai][bj][m][1];
;                     const u32x4 gw = *(const u32x4*)(G + ro + bj * HALF);
;                     float r[8]; const float a[8] = {v0[0], v0[1], v0[2], v0[3], v1[0], v1[1], v1[2], v1[3]};
; #pragma unroll
;                     for (int i = 0; i < 4; ++i) { const unsigned w = gw[i]; const float g0 = __builtin_bit_cast(float, w << 16), g1 = __builtin_bit_cast(float, w & 0xffff0000u);
;                         if (MODE == 0) { r[2 * i] = a[2 * i] * __builtin_amdgcn_rcpf(1.0f + __builtin_amdgcn_exp2f(-1.4426950408889634f * g0)); r[2 * i + 1] = a[2 * i + 1] * __builtin_amdgcn_rcpf(1.0f + __builtin_amdgcn_exp2f(-1.4426950408889634f * g1)); }
;                         else { r[2 * i] = g0 * a[2 * i] * __builtin_amdgcn_rcpf(1.0f + __builtin_amdgcn_exp2f(-1.4426950408889634f * a[2 * i])); r[2 * i + 1] = g1 * a[2 * i + 1] * __builtin_amdgcn_rcpf(1.0f + __builtin_amdgcn_exp2f(-1.4426950408889634f * a[2 * i + 1])); } }
;                     if (Add) { const u32x4 aw = *(const u32x4*)(Add + ro + bj * HALF);
; #pragma unroll
;                         for (int i = 0; i < 4; ++i) { const unsigned w = aw[i]; r[2 * i] += __builtin_bit_cast(float, w << 16); r[2 * i + 1] += __builtin_bit_cast(float, w & 0xffff0000u); } }
;                     u32x4 w; w.x = cvt_pk_bf16(r[0], r[1]); w.y = cvt_pk_bf16(r[2], r[3]); w.z = cvt_pk_bf16(r[4], r[5]); w.w = cvt_pk_bf16(r[6], r[7]);
;                     *(u32x4*)(O + ro + bj * HALF) = w; } }
.LBB0_887:
	s_lshl_b32 s17, s42, 8
	s_lshl_b32 s19, s43, 8
	s_cmp_gt_i32 s42, 63
	s_mov_b64 s[42:43], -1
	s_cbranch_scc0 .LBB0_890
	v_add_u32_e32 v131, s17, v158
	v_add_u32_e32 v132, s19, v157
	v_lshl_add_u32 v130, v131, 10, v132
	v_lshlrev_b32_e32 v130, 1, v130
	s_mov_b32 s100, 0xbfb8aa3b
	v_mov_b32_e32 v131, v130
	global_load_dwordx4 v[170:173], v131, s[10:11]
	global_load_dwordx4 v[174:177], v131, s[6:7]
	v_mov_b32_e32 v131, v130
	global_load_dwordx4 v[178:181], v131, s[10:11] offset:256
	global_load_dwordx4 v[182:185], v131, s[6:7] offset:256
	v_add_u32_e32 v131, 0x8000, v130
	global_load_dwordx4 v[186:189], v131, s[10:11]
	global_load_dwordx4 v[190:193], v131, s[6:7]
	v_add_u32_e32 v131, 0x8000, v130
	global_load_dwordx4 v[194:197], v131, s[10:11] offset:256
	global_load_dwordx4 v[198:201], v131, s[6:7] offset:256
	v_add_u32_e32 v131, 0x10000, v130
	global_load_dwordx4 v[202:205], v131, s[10:11]
	global_load_dwordx4 v[206:209], v131, s[6:7]
	s_waitcnt vmcnt(8)
	v_lshlrev_b32_e32 v146, 16, v170
	v_and_b32_e32 v147, 0xffff0000, v170
	v_lshlrev_b32_e32 v148, 16, v171
	v_and_b32_e32 v149, 0xffff0000, v171
	v_lshlrev_b32_e32 v150, 16, v172
	v_and_b32_e32 v151, 0xffff0000, v172
	v_lshlrev_b32_e32 v152, 16, v173
	v_and_b32_e32 v153, 0xffff0000, v173
	v_pk_mul_f32 v[146:147], v[146:147], s[100:101] op_sel_hi:[1,0]
	v_pk_mul_f32 v[148:149], v[148:149], s[100:101] op_sel_hi:[1,0]
	v_pk_mul_f32 v[150:151], v[150:151], s[100:101] op_sel_hi:[1,0]
	v_pk_mul_f32 v[152:153], v[152:153], s[100:101] op_sel_hi:[1,0]
	v_exp_f32_e32 v146, v146
	v_exp_f32_e32 v147, v147
	v_exp_f32_e32 v148, v148
	v_exp_f32_e32 v149, v149
	v_exp_f32_e32 v150, v150
	v_exp_f32_e32 v151, v151
	v_exp_f32_e32 v152, v152
	v_exp_f32_e32 v153, v153
	v_pk_add_f32 v[146:147], v[146:147], 1.0 op_sel_hi:[1,0]
	v_pk_add_f32 v[148:149], v[148:149], 1.0 op_sel_hi:[1,0]
	v_pk_add_f32 v[150:151], v[150:151], 1.0 op_sel_hi:[1,0]
	v_pk_add_f32 v[152:153], v[152:153], 1.0 op_sel_hi:[1,0]
	v_rcp_f32_e32 v146, v146
	v_rcp_f32_e32 v147, v147
	v_rcp_f32_e32 v148, v148
	v_rcp_f32_e32 v149, v149
	v_rcp_f32_e32 v150, v150
	v_rcp_f32_e32 v151, v151
	v_rcp_f32_e32 v152, v152
	v_rcp_f32_e32 v153, v153
	v_lshlrev_b32_e32 v162, 16, v174
	v_and_b32_e32 v163, 0xffff0000, v174
	v_lshlrev_b32_e32 v164, 16, v175
	v_and_b32_e32 v165, 0xffff0000, v175
	v_lshlrev_b32_e32 v166, 16, v176
	v_and_b32_e32 v167, 0xffff0000, v176
	v_lshlrev_b32_e32 v168, 16, v177
	v_and_b32_e32 v169, 0xffff0000, v177
	v_pk_fma_f32 v[162:163], v[126:127], v[146:147], v[162:163]
	v_pk_fma_f32 v[164:165], v[128:129], v[148:149], v[164:165]
	v_pk_fma_f32 v[166:167], v[122:123], v[150:151], v[166:167]
	v_pk_fma_f32 v[168:169], v[124:125], v[152:153], v[168:169]
	v_cvt_pk_bf16_f32 v162, v162, v163
	v_cvt_pk_bf16_f32 v163, v164, v165
	v_cvt_pk_bf16_f32 v164, v166, v167
	v_cvt_pk_bf16_f32 v165, v168, v169
	v_mov_b32_e32 v132, v130
	global_store_dwordx4 v132, v[162:165], s[8:9] sc1
	v_add_u32_e32 v131, 0x10000, v130
	global_load_dwordx4 v[170:173], v131, s[10:11] offset:256
	global_load_dwordx4 v[174:177], v131, s[6:7] offset:256
	s_waitcnt vmcnt(9)
	v_lshlrev_b32_e32 v146, 16, v178
	v_and_b32_e32 v147, 0xffff0000, v178
	v_lshlrev_b32_e32 v148, 16, v179
	v_and_b32_e32 v149, 0xffff0000, v179
	v_lshlrev_b32_e32 v150, 16, v180
	v_and_b32_e32 v151, 0xffff0000, v180
	v_lshlrev_b32_e32 v152, 16, v181
	v_and_b32_e32 v153, 0xffff0000, v181
	v_pk_mul_f32 v[146:147], v[146:147], s[100:101] op_sel_hi:[1,0]
	v_pk_mul_f32 v[148:149], v[148:149], s[100:101] op_sel_hi:[1,0]
	v_pk_mul_f32 v[150:151], v[150:151], s[100:101] op_sel_hi:[1,0]
	v_pk_mul_f32 v[152:153], v[152:153], s[100:101] op_sel_hi:[1,0]
	v_exp_f32_e32 v146, v146
	v_exp_f32_e32 v147, v147
	v_exp_f32_e32 v148, v148
	v_exp_f32_e32 v149, v149
	v_exp_f32_e32 v150, v150
	v_exp_f32_e32 v151, v151
	v_exp_f32_e32 v152, v152
	v_exp_f32_e32 v153, v153
	v_pk_add_f32 v[146:147], v[146:147], 1.0 op_sel_hi:[1,0]
	v_pk_add_f32 v[148:149], v[148:149], 1.0 op_sel_hi:[1,0]
	v_pk_add_f32 v[150:151], v[150:151], 1.0 op_sel_hi:[1,0]
	v_pk_add_f32 v[152:153], v[152:153], 1.0 op_sel_hi:[1,0]
	v_rcp_f32_e32 v146, v146
	v_rcp_f32_e32 v147, v147
	v_rcp_f32_e32 v148, v148
	v_rcp_f32_e32 v149, v149
	v_rcp_f32_e32 v150, v150
	v_rcp_f32_e32 v151, v151
	v_rcp_f32_e32 v152, v152
	v_rcp_f32_e32 v153, v153
	v_lshlrev_b32_e32 v162, 16, v182
	v_and_b32_e32 v163, 0xffff0000, v182
	v_lshlrev_b32_e32 v164, 16, v183
	v_and_b32_e32 v165, 0xffff0000, v183
	v_lshlrev_b32_e32 v166, 16, v184
	v_and_b32_e32 v167, 0xffff0000, v184
	v_lshlrev_b32_e32 v168, 16, v185
	v_and_b32_e32 v169, 0xffff0000, v185
	v_pk_fma_f32 v[162:163], v[118:119], v[146:147], v[162:163]
	v_pk_fma_f32 v[164:165], v[120:121], v[148:149], v[164:165]
	v_pk_fma_f32 v[166:167], v[114:115], v[150:151], v[166:167]
	v_pk_fma_f32 v[168:169], v[116:117], v[152:153], v[168:169]
	v_cvt_pk_bf16_f32 v162, v162, v163
	v_cvt_pk_bf16_f32 v163, v164, v165
	v_cvt_pk_bf16_f32 v164, v166, v167
	v_cvt_pk_bf16_f32 v165, v168, v169
	v_mov_b32_e32 v132, v130
	global_store_dwordx4 v132, v[162:165], s[8:9] offset:256 sc1
	v_add_u32_e32 v131, 0x18000, v130
	global_load_dwordx4 v[178:181], v131, s[10:11]
	global_load_dwordx4 v[182:185], v131, s[6:7]
	s_waitcnt vmcnt(10)
; __device__ __forceinline__ unsigned cvt_pk_bf16(float lo, float hi) { unsigned r; asm volatile("v_cvt_pk_bf16_f32 %0, %1, %2" : "=v"(r) : "v"(lo), "v"(hi)); return r; }
;     __device__ __forceinline__ void operator()(const f32x4 (&acc)[2][2][4][2], const Unit& u, int wr, int wc, int fr, int fq) const {
;     ...
;             for (int m = 0; m < 4; ++m) { const size_t ro = (size_t)(row0 + ai * HALF + m * 16) * ldc + col0;
; #pragma unroll
;                 for (int bj = 0; bj < 2; ++bj) { const f32x4 v0 = acc[ai][bj][m][0], v1 = acc[ai][bj][m][1];
;                     const u32x4 gw = *(const u32x4*)(G + ro + bj * HALF);
;                     float r[8]; const float a[8] = {v0[0], v0[1], v0[2], v0[3], v1[0], v1[1], v1[2], v1[3]};
; #pragma unroll
;                     for (int i = 0; i < 4; ++i) { const unsigned w = gw[i]; const float g0 = __builtin_bit_cast(float, w << 16), g1 = __builtin_bit_cast(float, w & 0xffff0000u);
;                         if (MODE == 0) { r[2 * i] = a[2 * i] * __builtin_amdgcn_rcpf(1.0f + __builtin_amdgcn_exp2f(-1.4426950408889634f * g0)); r[2 * i + 1] = a[2 * i + 1] * __builtin_amdgcn_rcpf(1.0f + __builtin_amdgcn_exp2f(-1.4426950408889634f * g1)); }
;                         else { r[2 * i] = g0 * a[2 * i] * __builtin_amdgcn_rcpf(1.0f + __builtin_amdgcn_exp2f(-1.4426950408889634f * a[2 * i])); r[2 * i + 1] = g1 * a[2 * i + 1] * __builtin_amdgcn_rcpf(1.0f + __builtin_amdgcn_exp2f(-1.4426950408889634f * a[2 * i + 1])); } }
;                     if (Add) { const u32x4 aw = *(const u32x4*)(Add + ro + bj * HALF);
; #pragma unroll
;                         for (int i = 0; i < 4; ++i) { const unsigned w = aw[i]; r[2 * i] += __builtin_bit_cast(float, w << 16); r[2 * i + 1] += __builtin_bit_cast(float, w & 0xffff0000u); } }
;                     u32x4 w; w.x = cvt_pk_bf16(r[0], r[1]); w.y = cvt_pk_bf16(r[2], r[3]); w.z = cvt_pk_bf16(r[4], r[5]); w.w = cvt_pk_bf16(r[6], r[7]);
;                     *(u32x4*)(O + ro + bj * HALF) = w; } }
	v_lshlrev_b32_e32 v146, 16, v186
	v_and_b32_e32 v147, 0xffff0000, v186
	v_lshlrev_b32_e32 v148, 16, v187
	v_and_b32_e32 v149, 0xffff0000, v187
	v_lshlrev_b32_e32 v150, 16, v188
	v_and_b32_e32 v151, 0xffff0000, v188
	v_lshlrev_b32_e32 v152, 16, v189
	v_and_b32_e32 v153, 0xffff0000, v189
	v_pk_mul_f32 v[146:147], v[146:147], s[100:101] op_sel_hi:[1,0]
	v_pk_mul_f32 v[148:149], v[148:149], s[100:101] op_sel_hi:[1,0]
	v_pk_mul_f32 v[150:151], v[150:151], s[100:101] op_sel_hi:[1,0]
	v_pk_mul_f32 v[152:153], v[152:153], s[100:101] op_sel_hi:[1,0]
	v_exp_f32_e32 v146, v146
	v_exp_f32_e32 v147, v147
	v_exp_f32_e32 v148, v148
	v_exp_f32_e32 v149, v149
	v_exp_f32_e32 v150, v150
	v_exp_f32_e32 v151, v151
	v_exp_f32_e32 v152, v152
	v_exp_f32_e32 v153, v153
	v_pk_add_f32 v[146:147], v[146:147], 1.0 op_sel_hi:[1,0]
	v_pk_add_f32 v[148:149], v[148:149], 1.0 op_sel_hi:[1,0]
	v_pk_add_f32 v[150:151], v[150:151], 1.0 op_sel_hi:[1,0]
	v_pk_add_f32 v[152:153], v[152:153], 1.0 op_sel_hi:[1,0]
	v_rcp_f32_e32 v146, v146
	v_rcp_f32_e32 v147, v147
	v_rcp_f32_e32 v148, v148
	v_rcp_f32_e32 v149, v149
	v_rcp_f32_e32 v150, v150
	v_rcp_f32_e32 v151, v151
	v_rcp_f32_e32 v152, v152
	v_rcp_f32_e32 v153, v153
	v_lshlrev_b32_e32 v162, 16, v190
	v_and_b32_e32 v163, 0xffff0000, v190
	v_lshlrev_b32_e32 v164, 16, v191
	v_and_b32_e32 v165, 0xffff0000, v191
	v_lshlrev_b32_e32 v166, 16, v192
	v_and_b32_e32 v167, 0xffff0000, v192
	v_lshlrev_b32_e32 v168, 16, v193
	v_and_b32_e32 v169, 0xffff0000, v193
	v_pk_fma_f32 v[162:163], v[110:111], v[146:147], v[162:163]
	v_pk_fma_f32 v[164:165], v[112:113], v[148:149], v[164:165]
	v_pk_fma_f32 v[166:167], v[106:107], v[150:151], v[166:167]
	v_pk_fma_f32 v[168:169], v[108:109], v[152:153], v[168:169]
	v_cvt_pk_bf16_f32 v162, v162, v163
	v_cvt_pk_bf16_f32 v163, v164, v165
	v_cvt_pk_bf16_f32 v164, v166, v167
	v_cvt_pk_bf16_f32 v165, v168, v169
	v_add_u32_e32 v132, 0x8000, v130
	global_store_dwordx4 v132, v[162:165], s[8:9] sc1
	v_add_u32_e32 v131, 0x18000, v130
	global_load_dwordx4 v[186:189], v131, s[10:11] offset:256
	global_load_dwordx4 v[190:193], v131, s[6:7] offset:256
	s_waitcnt vmcnt(11)
	v_lshlrev_b32_e32 v146, 16, v194
	v_and_b32_e32 v147, 0xffff0000, v194
	v_lshlrev_b32_e32 v148, 16, v195
	v_and_b32_e32 v149, 0xffff0000, v195
	v_lshlrev_b32_e32 v150, 16, v196
	v_and_b32_e32 v151, 0xffff0000, v196
	v_lshlrev_b32_e32 v152, 16, v197
	v_and_b32_e32 v153, 0xffff0000, v197
	v_pk_mul_f32 v[146:147], v[146:147], s[100:101] op_sel_hi:[1,0]
	v_pk_mul_f32 v[148:149], v[148:149], s[100:101] op_sel_hi:[1,0]
	v_pk_mul_f32 v[150:151], v[150:151], s[100:101] op_sel_hi:[1,0]
	v_pk_mul_f32 v[152:153], v[152:153], s[100:101] op_sel_hi:[1,0]
	v_exp_f32_e32 v146, v146
	v_exp_f32_e32 v147, v147
	v_exp_f32_e32 v148, v148
	v_exp_f32_e32 v149, v149
	v_exp_f32_e32 v150, v150
	v_exp_f32_e32 v151, v151
	v_exp_f32_e32 v152, v152
	v_exp_f32_e32 v153, v153
	v_pk_add_f32 v[146:147], v[146:147], 1.0 op_sel_hi:[1,0]
	v_pk_add_f32 v[148:149], v[148:149], 1.0 op_sel_hi:[1,0]
	v_pk_add_f32 v[150:151], v[150:151], 1.0 op_sel_hi:[1,0]
	v_pk_add_f32 v[152:153], v[152:153], 1.0 op_sel_hi:[1,0]
	v_rcp_f32_e32 v146, v146
	v_rcp_f32_e32 v147, v147
	v_rcp_f32_e32 v148, v148
	v_rcp_f32_e32 v149, v149
	v_rcp_f32_e32 v150, v150
	v_rcp_f32_e32 v151, v151
	v_rcp_f32_e32 v152, v152
	v_rcp_f32_e32 v153, v153
	v_lshlrev_b32_e32 v162, 16, v198
	v_and_b32_e32 v163, 0xffff0000, v198
	v_lshlrev_b32_e32 v164, 16, v199
	v_and_b32_e32 v165, 0xffff0000, v199
	v_lshlrev_b32_e32 v166, 16, v200
	v_and_b32_e32 v167, 0xffff0000, v200
	v_lshlrev_b32_e32 v168, 16, v201
	v_and_b32_e32 v169, 0xffff0000, v201
	v_pk_fma_f32 v[162:163], v[102:103], v[146:147], v[162:163]
	v_pk_fma_f32 v[164:165], v[104:105], v[148:149], v[164:165]
	v_pk_fma_f32 v[166:167], v[98:99], v[150:151], v[166:167]
	v_pk_fma_f32 v[168:169], v[100:101], v[152:153], v[168:169]
	v_cvt_pk_bf16_f32 v162, v162, v163
	v_cvt_pk_bf16_f32 v163, v164, v165
	v_cvt_pk_bf16_f32 v164, v166, v167
	v_cvt_pk_bf16_f32 v165, v168, v169
	v_add_u32_e32 v132, 0x8000, v130
	global_store_dwordx4 v132, v[162:165], s[8:9] offset:256 sc1
	v_add_u32_e32 v131, 0x40000, v130
	global_load_dwordx4 v[194:197], v131, s[10:11]
	global_load_dwordx4 v[198:201], v131, s[6:7]
	s_waitcnt vmcnt(12)
	v_lshlrev_b32_e32 v146, 16, v202
	v_and_b32_e32 v147, 0xffff0000, v202
	v_lshlrev_b32_e32 v148, 16, v203
	v_and_b32_e32 v149, 0xffff0000, v203
	v_lshlrev_b32_e32 v150, 16, v204
	v_and_b32_e32 v151, 0xffff0000, v204
	v_lshlrev_b32_e32 v152, 16, v205
	v_and_b32_e32 v153, 0xffff0000, v205
	v_pk_mul_f32 v[146:147], v[146:147], s[100:101] op_sel_hi:[1,0]
	v_pk_mul_f32 v[148:149], v[148:149], s[100:101] op_sel_hi:[1,0]
	v_pk_mul_f32 v[150:151], v[150:151], s[100:101] op_sel_hi:[1,0]
	v_pk_mul_f32 v[152:153], v[152:153], s[100:101] op_sel_hi:[1,0]
	v_exp_f32_e32 v146, v146
	v_exp_f32_e32 v147, v147
	v_exp_f32_e32 v148, v148
	v_exp_f32_e32 v149, v149
	v_exp_f32_e32 v150, v150
	v_exp_f32_e32 v151, v151
	v_exp_f32_e32 v152, v152
	v_exp_f32_e32 v153, v153
	v_pk_add_f32 v[146:147], v[146:147], 1.0 op_sel_hi:[1,0]
	v_pk_add_f32 v[148:149], v[148:149], 1.0 op_sel_hi:[1,0]
	v_pk_add_f32 v[150:151], v[150:151], 1.0 op_sel_hi:[1,0]
	v_pk_add_f32 v[152:153], v[152:153], 1.0 op_sel_hi:[1,0]
	v_rcp_f32_e32 v146, v146
	v_rcp_f32_e32 v147, v147
	v_rcp_f32_e32 v148, v148
	v_rcp_f32_e32 v149, v149
	v_rcp_f32_e32 v150, v150
	v_rcp_f32_e32 v151, v151
	v_rcp_f32_e32 v152, v152
	v_rcp_f32_e32 v153, v153
	v_lshlrev_b32_e32 v162, 16, v206
	v_and_b32_e32 v163, 0xffff0000, v206
	v_lshlrev_b32_e32 v164, 16, v207
	v_and_b32_e32 v165, 0xffff0000, v207
	v_lshlrev_b32_e32 v166, 16, v208
	v_and_b32_e32 v167, 0xffff0000, v208
	v_lshlrev_b32_e32 v168, 16, v209
	v_and_b32_e32 v169, 0xffff0000, v209
	v_pk_fma_f32 v[162:163], v[94:95], v[146:147], v[162:163]
	v_pk_fma_f32 v[164:165], v[96:97], v[148:149], v[164:165]
	v_pk_fma_f32 v[166:167], v[90:91], v[150:151], v[166:167]
	v_pk_fma_f32 v[168:169], v[92:93], v[152:153], v[168:169]
	v_cvt_pk_bf16_f32 v162, v162, v163
	v_cvt_pk_bf16_f32 v163, v164, v165
	v_cvt_pk_bf16_f32 v164, v166, v167
	v_cvt_pk_bf16_f32 v165, v168, v169
	v_add_u32_e32 v132, 0x10000, v130
	global_store_dwordx4 v132, v[162:165], s[8:9] sc1
	v_add_u32_e32 v131, 0x40000, v130
	global_load_dwordx4 v[202:205], v131, s[10:11] offset:256
	global_load_dwordx4 v[206:209], v131, s[6:7] offset:256
	s_waitcnt vmcnt(12)
; __device__ __forceinline__ unsigned cvt_pk_bf16(float lo, float hi) { unsigned r; asm volatile("v_cvt_pk_bf16_f32 %0, %1, %2" : "=v"(r) : "v"(lo), "v"(hi)); return r; }
;     __device__ __forceinline__ void operator()(const f32x4 (&acc)[2][2][4][2], const Unit& u, int wr, int wc, int fr, int fq) const {
;     ...
;             for (int m = 0; m < 4; ++m) { const size_t ro = (size_t)(row0 + ai * HALF + m * 16) * ldc + col0;
; #pragma unroll
;                 for (int bj = 0; bj < 2; ++bj) { const f32x4 v0 = acc[ai][bj][m][0], v1 = acc[ai][bj][m][1];
;                     const u32x4 gw = *(const u32x4*)(G + ro + bj * HALF);
;                     float r[8]; const float a[8] = {v0[0], v0[1], v0[2], v0[3], v1[0], v1[1], v1[2], v1[3]};
; #pragma unroll
;                     for (int i = 0; i < 4; ++i) { const unsigned w = gw[i]; const float g0 = __builtin_bit_cast(float, w << 16), g1 = __builtin_bit_cast(float, w & 0xffff0000u);
;                         if (MODE == 0) { r[2 * i] = a[2 * i] * __builtin_amdgcn_rcpf(1.0f + __builtin_amdgcn_exp2f(-1.4426950408889634f * g0)); r[2 * i + 1] = a[2 * i + 1] * __builtin_amdgcn_rcpf(1.0f + __builtin_amdgcn_exp2f(-1.4426950408889634f * g1)); }
;                         else { r[2 * i] = g0 * a[2 * i] * __builtin_amdgcn_rcpf(1.0f + __builtin_amdgcn_exp2f(-1.4426950408889634f * a[2 * i])); r[2 * i + 1] = g1 * a[2 * i + 1] * __builtin_amdgcn_rcpf(1.0f + __builtin_amdgcn_exp2f(-1.4426950408889634f * a[2 * i + 1])); } }
;                     if (Add) { const u32x4 aw = *(const u32x4*)(Add + ro + bj * HALF);
; #pragma unroll
;                         for (int i = 0; i < 4; ++i) { const unsigned w = aw[i]; r[2 * i] += __builtin_bit_cast(float, w << 16); r[2 * i + 1] += __builtin_bit_cast(float, w & 0xffff0000u); } }
;                     u32x4 w; w.x = cvt_pk_bf16(r[0], r[1]); w.y = cvt_pk_bf16(r[2], r[3]); w.z = cvt_pk_bf16(r[4], r[5]); w.w = cvt_pk_bf16(r[6], r[7]);
;                     *(u32x4*)(O + ro + bj * HALF) = w; } }
	v_lshlrev_b32_e32 v146, 16, v170
	v_and_b32_e32 v147, 0xffff0000, v170
	v_lshlrev_b32_e32 v148, 16, v171
	v_and_b32_e32 v149, 0xffff0000, v171
	v_lshlrev_b32_e32 v150, 16, v172
	v_and_b32_e32 v151, 0xffff0000, v172
	v_lshlrev_b32_e32 v152, 16, v173
	v_and_b32_e32 v153, 0xffff0000, v173
	v_pk_mul_f32 v[146:147], v[146:147], s[100:101] op_sel_hi:[1,0]
	v_pk_mul_f32 v[148:149], v[148:149], s[100:101] op_sel_hi:[1,0]
	v_pk_mul_f32 v[150:151], v[150:151], s[100:101] op_sel_hi:[1,0]
	v_pk_mul_f32 v[152:153], v[152:153], s[100:101] op_sel_hi:[1,0]
	v_exp_f32_e32 v146, v146
	v_exp_f32_e32 v147, v147
	v_exp_f32_e32 v148, v148
	v_exp_f32_e32 v149, v149
	v_exp_f32_e32 v150, v150
	v_exp_f32_e32 v151, v151
	v_exp_f32_e32 v152, v152
	v_exp_f32_e32 v153, v153
	v_pk_add_f32 v[146:147], v[146:147], 1.0 op_sel_hi:[1,0]
	v_pk_add_f32 v[148:149], v[148:149], 1.0 op_sel_hi:[1,0]
	v_pk_add_f32 v[150:151], v[150:151], 1.0 op_sel_hi:[1,0]
	v_pk_add_f32 v[152:153], v[152:153], 1.0 op_sel_hi:[1,0]
	v_rcp_f32_e32 v146, v146
	v_rcp_f32_e32 v147, v147
	v_rcp_f32_e32 v148, v148
	v_rcp_f32_e32 v149, v149
	v_rcp_f32_e32 v150, v150
	v_rcp_f32_e32 v151, v151
	v_rcp_f32_e32 v152, v152
	v_rcp_f32_e32 v153, v153
	v_lshlrev_b32_e32 v162, 16, v174
	v_and_b32_e32 v163, 0xffff0000, v174
	v_lshlrev_b32_e32 v164, 16, v175
	v_and_b32_e32 v165, 0xffff0000, v175
	v_lshlrev_b32_e32 v166, 16, v176
	v_and_b32_e32 v167, 0xffff0000, v176
	v_lshlrev_b32_e32 v168, 16, v177
	v_and_b32_e32 v169, 0xffff0000, v177
	v_pk_fma_f32 v[162:163], v[86:87], v[146:147], v[162:163]
	v_pk_fma_f32 v[164:165], v[88:89], v[148:149], v[164:165]
	v_pk_fma_f32 v[166:167], v[82:83], v[150:151], v[166:167]
	v_pk_fma_f32 v[168:169], v[84:85], v[152:153], v[168:169]
	v_cvt_pk_bf16_f32 v162, v162, v163
	v_cvt_pk_bf16_f32 v163, v164, v165
	v_cvt_pk_bf16_f32 v164, v166, v167
	v_cvt_pk_bf16_f32 v165, v168, v169
	v_add_u32_e32 v132, 0x10000, v130
	global_store_dwordx4 v132, v[162:165], s[8:9] offset:256 sc1
	v_add_u32_e32 v131, 0x48000, v130
	global_load_dwordx4 v[170:173], v131, s[10:11]
	global_load_dwordx4 v[174:177], v131, s[6:7]
	s_waitcnt vmcnt(12)
	v_lshlrev_b32_e32 v146, 16, v178
	v_and_b32_e32 v147, 0xffff0000, v178
	v_lshlrev_b32_e32 v148, 16, v179
	v_and_b32_e32 v149, 0xffff0000, v179
	v_lshlrev_b32_e32 v150, 16, v180
	v_and_b32_e32 v151, 0xffff0000, v180
	v_lshlrev_b32_e32 v152, 16, v181
	v_and_b32_e32 v153, 0xffff0000, v181
	v_pk_mul_f32 v[146:147], v[146:147], s[100:101] op_sel_hi:[1,0]
	v_pk_mul_f32 v[148:149], v[148:149], s[100:101] op_sel_hi:[1,0]
	v_pk_mul_f32 v[150:151], v[150:151], s[100:101] op_sel_hi:[1,0]
	v_pk_mul_f32 v[152:153], v[152:153], s[100:101] op_sel_hi:[1,0]
	v_exp_f32_e32 v146, v146
	v_exp_f32_e32 v147, v147
	v_exp_f32_e32 v148, v148
	v_exp_f32_e32 v149, v149
	v_exp_f32_e32 v150, v150
	v_exp_f32_e32 v151, v151
	v_exp_f32_e32 v152, v152
	v_exp_f32_e32 v153, v153
	v_pk_add_f32 v[146:147], v[146:147], 1.0 op_sel_hi:[1,0]
	v_pk_add_f32 v[148:149], v[148:149], 1.0 op_sel_hi:[1,0]
	v_pk_add_f32 v[150:151], v[150:151], 1.0 op_sel_hi:[1,0]
	v_pk_add_f32 v[152:153], v[152:153], 1.0 op_sel_hi:[1,0]
	v_rcp_f32_e32 v146, v146
	v_rcp_f32_e32 v147, v147
	v_rcp_f32_e32 v148, v148
	v_rcp_f32_e32 v149, v149
	v_rcp_f32_e32 v150, v150
	v_rcp_f32_e32 v151, v151
	v_rcp_f32_e32 v152, v152
	v_rcp_f32_e32 v153, v153
	v_lshlrev_b32_e32 v162, 16, v182
	v_and_b32_e32 v163, 0xffff0000, v182
	v_lshlrev_b32_e32 v164, 16, v183
	v_and_b32_e32 v165, 0xffff0000, v183
	v_lshlrev_b32_e32 v166, 16, v184
	v_and_b32_e32 v167, 0xffff0000, v184
	v_lshlrev_b32_e32 v168, 16, v185
	v_and_b32_e32 v169, 0xffff0000, v185
	v_pk_fma_f32 v[162:163], v[78:79], v[146:147], v[162:163]
	v_pk_fma_f32 v[164:165], v[80:81], v[148:149], v[164:165]
	v_pk_fma_f32 v[166:167], v[74:75], v[150:151], v[166:167]
	v_pk_fma_f32 v[168:169], v[76:77], v[152:153], v[168:169]
	v_cvt_pk_bf16_f32 v162, v162, v163
	v_cvt_pk_bf16_f32 v163, v164, v165
	v_cvt_pk_bf16_f32 v164, v166, v167
	v_cvt_pk_bf16_f32 v165, v168, v169
	v_add_u32_e32 v132, 0x18000, v130
	global_store_dwordx4 v132, v[162:165], s[8:9] sc1
	v_add_u32_e32 v131, 0x48000, v130
	global_load_dwordx4 v[178:181], v131, s[10:11] offset:256
	global_load_dwordx4 v[182:185], v131, s[6:7] offset:256
	s_waitcnt vmcnt(12)
	v_lshlrev_b32_e32 v146, 16, v186
	v_and_b32_e32 v147, 0xffff0000, v186
	v_lshlrev_b32_e32 v148, 16, v187
	v_and_b32_e32 v149, 0xffff0000, v187
	v_lshlrev_b32_e32 v150, 16, v188
	v_and_b32_e32 v151, 0xffff0000, v188
	v_lshlrev_b32_e32 v152, 16, v189
	v_and_b32_e32 v153, 0xffff0000, v189
	v_pk_mul_f32 v[146:147], v[146:147], s[100:101] op_sel_hi:[1,0]
	v_pk_mul_f32 v[148:149], v[148:149], s[100:101] op_sel_hi:[1,0]
	v_pk_mul_f32 v[150:151], v[150:151], s[100:101] op_sel_hi:[1,0]
	v_pk_mul_f32 v[152:153], v[152:153], s[100:101] op_sel_hi:[1,0]
	v_exp_f32_e32 v146, v146
	v_exp_f32_e32 v147, v147
	v_exp_f32_e32 v148, v148
	v_exp_f32_e32 v149, v149
	v_exp_f32_e32 v150, v150
	v_exp_f32_e32 v151, v151
	v_exp_f32_e32 v152, v152
	v_exp_f32_e32 v153, v153
	v_pk_add_f32 v[146:147], v[146:147], 1.0 op_sel_hi:[1,0]
	v_pk_add_f32 v[148:149], v[148:149], 1.0 op_sel_hi:[1,0]
	v_pk_add_f32 v[150:151], v[150:151], 1.0 op_sel_hi:[1,0]
	v_pk_add_f32 v[152:153], v[152:153], 1.0 op_sel_hi:[1,0]
	v_rcp_f32_e32 v146, v146
	v_rcp_f32_e32 v147, v147
	v_rcp_f32_e32 v148, v148
	v_rcp_f32_e32 v149, v149
	v_rcp_f32_e32 v150, v150
	v_rcp_f32_e32 v151, v151
	v_rcp_f32_e32 v152, v152
	v_rcp_f32_e32 v153, v153
	v_lshlrev_b32_e32 v162, 16, v190
	v_and_b32_e32 v163, 0xffff0000, v190
	v_lshlrev_b32_e32 v164, 16, v191
	v_and_b32_e32 v165, 0xffff0000, v191
	v_lshlrev_b32_e32 v166, 16, v192
	v_and_b32_e32 v167, 0xffff0000, v192
	v_lshlrev_b32_e32 v168, 16, v193
	v_and_b32_e32 v169, 0xffff0000, v193
	v_pk_fma_f32 v[162:163], v[70:71], v[146:147], v[162:163]
	v_pk_fma_f32 v[164:165], v[72:73], v[148:149], v[164:165]
	v_pk_fma_f32 v[166:167], v[66:67], v[150:151], v[166:167]
	v_pk_fma_f32 v[168:169], v[68:69], v[152:153], v[168:169]
	v_cvt_pk_bf16_f32 v162, v162, v163
	v_cvt_pk_bf16_f32 v163, v164, v165
	v_cvt_pk_bf16_f32 v164, v166, v167
	v_cvt_pk_bf16_f32 v165, v168, v169
	v_add_u32_e32 v132, 0x18000, v130
	global_store_dwordx4 v132, v[162:165], s[8:9] offset:256 sc1
	v_add_u32_e32 v131, 0x50000, v130
	global_load_dwordx4 v[186:189], v131, s[10:11]
	global_load_dwordx4 v[190:193], v131, s[6:7]
	s_waitcnt vmcnt(12)
; __device__ __forceinline__ unsigned cvt_pk_bf16(float lo, float hi) { unsigned r; asm volatile("v_cvt_pk_bf16_f32 %0, %1, %2" : "=v"(r) : "v"(lo), "v"(hi)); return r; }
;     __device__ __forceinline__ void operator()(const f32x4 (&acc)[2][2][4][2], const Unit& u, int wr, int wc, int fr, int fq) const {
;     ...
;             for (int m = 0; m < 4; ++m) { const size_t ro = (size_t)(row0 + ai * HALF + m * 16) * ldc + col0;
; #pragma unroll
;                 for (int bj = 0; bj < 2; ++bj) { const f32x4 v0 = acc[ai][bj][m][0], v1 = acc[ai][bj][m][1];
;                     const u32x4 gw = *(const u32x4*)(G + ro + bj * HALF);
;                     float r[8]; const float a[8] = {v0[0], v0[1], v0[2], v0[3], v1[0], v1[1], v1[2], v1[3]};
; #pragma unroll
;                     for (int i = 0; i < 4; ++i) { const unsigned w = gw[i]; const float g0 = __builtin_bit_cast(float, w << 16), g1 = __builtin_bit_cast(float, w & 0xffff0000u);
;                         if (MODE == 0) { r[2 * i] = a[2 * i] * __builtin_amdgcn_rcpf(1.0f + __builtin_amdgcn_exp2f(-1.4426950408889634f * g0)); r[2 * i + 1] = a[2 * i + 1] * __builtin_amdgcn_rcpf(1.0f + __builtin_amdgcn_exp2f(-1.4426950408889634f * g1)); }
;                         else { r[2 * i] = g0 * a[2 * i] * __builtin_amdgcn_rcpf(1.0f + __builtin_amdgcn_exp2f(-1.4426950408889634f * a[2 * i])); r[2 * i + 1] = g1 * a[2 * i + 1] * __builtin_amdgcn_rcpf(1.0f + __builtin_amdgcn_exp2f(-1.4426950408889634f * a[2 * i + 1])); } }
;                     if (Add) { const u32x4 aw = *(const u32x4*)(Add + ro + bj * HALF);
; #pragma unroll
;                         for (int i = 0; i < 4; ++i) { const unsigned w = aw[i]; r[2 * i] += __builtin_bit_cast(float, w << 16); r[2 * i + 1] += __builtin_bit_cast(float, w & 0xffff0000u); } }
;                     u32x4 w; w.x = cvt_pk_bf16(r[0], r[1]); w.y = cvt_pk_bf16(r[2], r[3]); w.z = cvt_pk_bf16(r[4], r[5]); w.w = cvt_pk_bf16(r[6], r[7]);
;                     *(u32x4*)(O + ro + bj * HALF) = w; } }
	v_lshlrev_b32_e32 v146, 16, v194
	v_and_b32_e32 v147, 0xffff0000, v194
	v_lshlrev_b32_e32 v148, 16, v195
	v_and_b32_e32 v149, 0xffff0000, v195
	v_lshlrev_b32_e32 v150, 16, v196
	v_and_b32_e32 v151, 0xffff0000, v196
	v_lshlrev_b32_e32 v152, 16, v197
	v_and_b32_e32 v153, 0xffff0000, v197
	v_pk_mul_f32 v[146:147], v[146:147], s[100:101] op_sel_hi:[1,0]
	v_pk_mul_f32 v[148:149], v[148:149], s[100:101] op_sel_hi:[1,0]
	v_pk_mul_f32 v[150:151], v[150:151], s[100:101] op_sel_hi:[1,0]
	v_pk_mul_f32 v[152:153], v[152:153], s[100:101] op_sel_hi:[1,0]
	v_exp_f32_e32 v146, v146
	v_exp_f32_e32 v147, v147
	v_exp_f32_e32 v148, v148
	v_exp_f32_e32 v149, v149
	v_exp_f32_e32 v150, v150
	v_exp_f32_e32 v151, v151
	v_exp_f32_e32 v152, v152
	v_exp_f32_e32 v153, v153
	v_pk_add_f32 v[146:147], v[146:147], 1.0 op_sel_hi:[1,0]
	v_pk_add_f32 v[148:149], v[148:149], 1.0 op_sel_hi:[1,0]
	v_pk_add_f32 v[150:151], v[150:151], 1.0 op_sel_hi:[1,0]
	v_pk_add_f32 v[152:153], v[152:153], 1.0 op_sel_hi:[1,0]
	v_rcp_f32_e32 v146, v146
	v_rcp_f32_e32 v147, v147
	v_rcp_f32_e32 v148, v148
	v_rcp_f32_e32 v149, v149
	v_rcp_f32_e32 v150, v150
	v_rcp_f32_e32 v151, v151
	v_rcp_f32_e32 v152, v152
	v_rcp_f32_e32 v153, v153
	v_lshlrev_b32_e32 v162, 16, v198
	v_and_b32_e32 v163, 0xffff0000, v198
	v_lshlrev_b32_e32 v164, 16, v199
	v_and_b32_e32 v165, 0xffff0000, v199
	v_lshlrev_b32_e32 v166, 16, v200
	v_and_b32_e32 v167, 0xffff0000, v200
	v_lshlrev_b32_e32 v168, 16, v201
	v_and_b32_e32 v169, 0xffff0000, v201
	v_pk_fma_f32 v[162:163], v[62:63], v[146:147], v[162:163]
	v_pk_fma_f32 v[164:165], v[64:65], v[148:149], v[164:165]
	v_pk_fma_f32 v[166:167], v[58:59], v[150:151], v[166:167]
	v_pk_fma_f32 v[168:169], v[60:61], v[152:153], v[168:169]
	v_cvt_pk_bf16_f32 v162, v162, v163
	v_cvt_pk_bf16_f32 v163, v164, v165
	v_cvt_pk_bf16_f32 v164, v166, v167
	v_cvt_pk_bf16_f32 v165, v168, v169
	v_add_u32_e32 v132, 0x40000, v130
	global_store_dwordx4 v132, v[162:165], s[8:9] sc1
	v_add_u32_e32 v131, 0x50000, v130
	global_load_dwordx4 v[194:197], v131, s[10:11] offset:256
	global_load_dwordx4 v[198:201], v131, s[6:7] offset:256
	s_waitcnt vmcnt(12)
	v_lshlrev_b32_e32 v146, 16, v202
	v_and_b32_e32 v147, 0xffff0000, v202
	v_lshlrev_b32_e32 v148, 16, v203
	v_and_b32_e32 v149, 0xffff0000, v203
	v_lshlrev_b32_e32 v150, 16, v204
	v_and_b32_e32 v151, 0xffff0000, v204
	v_lshlrev_b32_e32 v152, 16, v205
	v_and_b32_e32 v153, 0xffff0000, v205
	v_pk_mul_f32 v[146:147], v[146:147], s[100:101] op_sel_hi:[1,0]
	v_pk_mul_f32 v[148:149], v[148:149], s[100:101] op_sel_hi:[1,0]
	v_pk_mul_f32 v[150:151], v[150:151], s[100:101] op_sel_hi:[1,0]
	v_pk_mul_f32 v[152:153], v[152:153], s[100:101] op_sel_hi:[1,0]
	v_exp_f32_e32 v146, v146
	v_exp_f32_e32 v147, v147
	v_exp_f32_e32 v148, v148
	v_exp_f32_e32 v149, v149
	v_exp_f32_e32 v150, v150
	v_exp_f32_e32 v151, v151
	v_exp_f32_e32 v152, v152
	v_exp_f32_e32 v153, v153
	v_pk_add_f32 v[146:147], v[146:147], 1.0 op_sel_hi:[1,0]
	v_pk_add_f32 v[148:149], v[148:149], 1.0 op_sel_hi:[1,0]
	v_pk_add_f32 v[150:151], v[150:151], 1.0 op_sel_hi:[1,0]
	v_pk_add_f32 v[152:153], v[152:153], 1.0 op_sel_hi:[1,0]
	v_rcp_f32_e32 v146, v146
	v_rcp_f32_e32 v147, v147
	v_rcp_f32_e32 v148, v148
	v_rcp_f32_e32 v149, v149
	v_rcp_f32_e32 v150, v150
	v_rcp_f32_e32 v151, v151
	v_rcp_f32_e32 v152, v152
	v_rcp_f32_e32 v153, v153
	v_lshlrev_b32_e32 v162, 16, v206
	v_and_b32_e32 v163, 0xffff0000, v206
	v_lshlrev_b32_e32 v164, 16, v207
	v_and_b32_e32 v165, 0xffff0000, v207
	v_lshlrev_b32_e32 v166, 16, v208
	v_and_b32_e32 v167, 0xffff0000, v208
	v_lshlrev_b32_e32 v168, 16, v209
	v_and_b32_e32 v169, 0xffff0000, v209
	v_pk_fma_f32 v[162:163], v[54:55], v[146:147], v[162:163]
	v_pk_fma_f32 v[164:165], v[56:57], v[148:149], v[164:165]
	v_pk_fma_f32 v[166:167], v[50:51], v[150:151], v[166:167]
	v_pk_fma_f32 v[168:169], v[52:53], v[152:153], v[168:169]
	v_cvt_pk_bf16_f32 v162, v162, v163
	v_cvt_pk_bf16_f32 v163, v164, v165
	v_cvt_pk_bf16_f32 v164, v166, v167
	v_cvt_pk_bf16_f32 v165, v168, v169
	v_add_u32_e32 v132, 0x40000, v130
	global_store_dwordx4 v132, v[162:165], s[8:9] offset:256 sc1
	v_add_u32_e32 v131, 0x58000, v130
	global_load_dwordx4 v[202:205], v131, s[10:11]
	global_load_dwordx4 v[206:209], v131, s[6:7]
	s_waitcnt vmcnt(12)
	v_lshlrev_b32_e32 v146, 16, v170
	v_and_b32_e32 v147, 0xffff0000, v170
	v_lshlrev_b32_e32 v148, 16, v171
	v_and_b32_e32 v149, 0xffff0000, v171
	v_lshlrev_b32_e32 v150, 16, v172
	v_and_b32_e32 v151, 0xffff0000, v172
	v_lshlrev_b32_e32 v152, 16, v173
	v_and_b32_e32 v153, 0xffff0000, v173
	v_pk_mul_f32 v[146:147], v[146:147], s[100:101] op_sel_hi:[1,0]
	v_pk_mul_f32 v[148:149], v[148:149], s[100:101] op_sel_hi:[1,0]
	v_pk_mul_f32 v[150:151], v[150:151], s[100:101] op_sel_hi:[1,0]
	v_pk_mul_f32 v[152:153], v[152:153], s[100:101] op_sel_hi:[1,0]
	v_exp_f32_e32 v146, v146
	v_exp_f32_e32 v147, v147
	v_exp_f32_e32 v148, v148
	v_exp_f32_e32 v149, v149
	v_exp_f32_e32 v150, v150
	v_exp_f32_e32 v151, v151
	v_exp_f32_e32 v152, v152
	v_exp_f32_e32 v153, v153
	v_pk_add_f32 v[146:147], v[146:147], 1.0 op_sel_hi:[1,0]
	v_pk_add_f32 v[148:149], v[148:149], 1.0 op_sel_hi:[1,0]
	v_pk_add_f32 v[150:151], v[150:151], 1.0 op_sel_hi:[1,0]
	v_pk_add_f32 v[152:153], v[152:153], 1.0 op_sel_hi:[1,0]
	v_rcp_f32_e32 v146, v146
	v_rcp_f32_e32 v147, v147
	v_rcp_f32_e32 v148, v148
	v_rcp_f32_e32 v149, v149
	v_rcp_f32_e32 v150, v150
	v_rcp_f32_e32 v151, v151
	v_rcp_f32_e32 v152, v152
	v_rcp_f32_e32 v153, v153
	v_lshlrev_b32_e32 v162, 16, v174
	v_and_b32_e32 v163, 0xffff0000, v174
	v_lshlrev_b32_e32 v164, 16, v175
	v_and_b32_e32 v165, 0xffff0000, v175
	v_lshlrev_b32_e32 v166, 16, v176
	v_and_b32_e32 v167, 0xffff0000, v176
	v_lshlrev_b32_e32 v168, 16, v177
	v_and_b32_e32 v169, 0xffff0000, v177
	v_pk_fma_f32 v[162:163], v[46:47], v[146:147], v[162:163]
	v_pk_fma_f32 v[164:165], v[48:49], v[148:149], v[164:165]
	v_pk_fma_f32 v[166:167], v[42:43], v[150:151], v[166:167]
	v_pk_fma_f32 v[168:169], v[44:45], v[152:153], v[168:169]
	v_cvt_pk_bf16_f32 v162, v162, v163
	v_cvt_pk_bf16_f32 v163, v164, v165
	v_cvt_pk_bf16_f32 v164, v166, v167
	v_cvt_pk_bf16_f32 v165, v168, v169
	v_add_u32_e32 v132, 0x48000, v130
	global_store_dwordx4 v132, v[162:165], s[8:9] sc1
	v_add_u32_e32 v131, 0x58000, v130
	global_load_dwordx4 v[170:173], v131, s[10:11] offset:256
	global_load_dwordx4 v[174:177], v131, s[6:7] offset:256
	s_waitcnt vmcnt(12)
; __device__ __forceinline__ unsigned cvt_pk_bf16(float lo, float hi) { unsigned r; asm volatile("v_cvt_pk_bf16_f32 %0, %1, %2" : "=v"(r) : "v"(lo), "v"(hi)); return r; }
;     __device__ __forceinline__ void operator()(const f32x4 (&acc)[2][2][4][2], const Unit& u, int wr, int wc, int fr, int fq) const {
;     ...
;             for (int m = 0; m < 4; ++m) { const size_t ro = (size_t)(row0 + ai * HALF + m * 16) * ldc + col0;
; #pragma unroll
;                 for (int bj = 0; bj < 2; ++bj) { const f32x4 v0 = acc[ai][bj][m][0], v1 = acc[ai][bj][m][1];
;                     const u32x4 gw = *(const u32x4*)(G + ro + bj * HALF);
;                     float r[8]; const float a[8] = {v0[0], v0[1], v0[2], v0[3], v1[0], v1[1], v1[2], v1[3]};
; #pragma unroll
;                     for (int i = 0; i < 4; ++i) { const unsigned w = gw[i]; const float g0 = __builtin_bit_cast(float, w << 16), g1 = __builtin_bit_cast(float, w & 0xffff0000u);
;                         if (MODE == 0) { r[2 * i] = a[2 * i] * __builtin_amdgcn_rcpf(1.0f + __builtin_amdgcn_exp2f(-1.4426950408889634f * g0)); r[2 * i + 1] = a[2 * i + 1] * __builtin_amdgcn_rcpf(1.0f + __builtin_amdgcn_exp2f(-1.4426950408889634f * g1)); }
;                         else { r[2 * i] = g0 * a[2 * i] * __builtin_amdgcn_rcpf(1.0f + __builtin_amdgcn_exp2f(-1.4426950408889634f * a[2 * i])); r[2 * i + 1] = g1 * a[2 * i + 1] * __builtin_amdgcn_rcpf(1.0f + __builtin_amdgcn_exp2f(-1.4426950408889634f * a[2 * i + 1])); } }
;                     if (Add) { const u32x4 aw = *(const u32x4*)(Add + ro + bj * HALF);
; #pragma unroll
;                         for (int i = 0; i < 4; ++i) { const unsigned w = aw[i]; r[2 * i] += __builtin_bit_cast(float, w << 16); r[2 * i + 1] += __builtin_bit_cast(float, w & 0xffff0000u); } }
;                     u32x4 w; w.x = cvt_pk_bf16(r[0], r[1]); w.y = cvt_pk_bf16(r[2], r[3]); w.z = cvt_pk_bf16(r[4], r[5]); w.w = cvt_pk_bf16(r[6], r[7]);
;                     *(u32x4*)(O + ro + bj * HALF) = w; } }
	v_lshlrev_b32_e32 v146, 16, v178
	v_and_b32_e32 v147, 0xffff0000, v178
	v_lshlrev_b32_e32 v148, 16, v179
	v_and_b32_e32 v149, 0xffff0000, v179
	v_lshlrev_b32_e32 v150, 16, v180
	v_and_b32_e32 v151, 0xffff0000, v180
	v_lshlrev_b32_e32 v152, 16, v181
	v_and_b32_e32 v153, 0xffff0000, v181
	v_pk_mul_f32 v[146:147], v[146:147], s[100:101] op_sel_hi:[1,0]
	v_pk_mul_f32 v[148:149], v[148:149], s[100:101] op_sel_hi:[1,0]
	v_pk_mul_f32 v[150:151], v[150:151], s[100:101] op_sel_hi:[1,0]
	v_pk_mul_f32 v[152:153], v[152:153], s[100:101] op_sel_hi:[1,0]
	v_exp_f32_e32 v146, v146
	v_exp_f32_e32 v147, v147
	v_exp_f32_e32 v148, v148
	v_exp_f32_e32 v149, v149
	v_exp_f32_e32 v150, v150
	v_exp_f32_e32 v151, v151
	v_exp_f32_e32 v152, v152
	v_exp_f32_e32 v153, v153
	v_pk_add_f32 v[146:147], v[146:147], 1.0 op_sel_hi:[1,0]
	v_pk_add_f32 v[148:149], v[148:149], 1.0 op_sel_hi:[1,0]
	v_pk_add_f32 v[150:151], v[150:151], 1.0 op_sel_hi:[1,0]
	v_pk_add_f32 v[152:153], v[152:153], 1.0 op_sel_hi:[1,0]
	v_rcp_f32_e32 v146, v146
	v_rcp_f32_e32 v147, v147
	v_rcp_f32_e32 v148, v148
	v_rcp_f32_e32 v149, v149
	v_rcp_f32_e32 v150, v150
	v_rcp_f32_e32 v151, v151
	v_rcp_f32_e32 v152, v152
	v_rcp_f32_e32 v153, v153
	v_lshlrev_b32_e32 v162, 16, v182
	v_and_b32_e32 v163, 0xffff0000, v182
	v_lshlrev_b32_e32 v164, 16, v183
	v_and_b32_e32 v165, 0xffff0000, v183
	v_lshlrev_b32_e32 v166, 16, v184
	v_and_b32_e32 v167, 0xffff0000, v184
	v_lshlrev_b32_e32 v168, 16, v185
	v_and_b32_e32 v169, 0xffff0000, v185
	v_pk_fma_f32 v[162:163], v[38:39], v[146:147], v[162:163]
	v_pk_fma_f32 v[164:165], v[40:41], v[148:149], v[164:165]
	v_pk_fma_f32 v[166:167], v[34:35], v[150:151], v[166:167]
	v_pk_fma_f32 v[168:169], v[36:37], v[152:153], v[168:169]
	v_cvt_pk_bf16_f32 v162, v162, v163
	v_cvt_pk_bf16_f32 v163, v164, v165
	v_cvt_pk_bf16_f32 v164, v166, v167
	v_cvt_pk_bf16_f32 v165, v168, v169
	v_add_u32_e32 v132, 0x48000, v130
	global_store_dwordx4 v132, v[162:165], s[8:9] offset:256 sc1
	s_waitcnt vmcnt(10)
	v_lshlrev_b32_e32 v146, 16, v186
	v_and_b32_e32 v147, 0xffff0000, v186
	v_lshlrev_b32_e32 v148, 16, v187
	v_and_b32_e32 v149, 0xffff0000, v187
	v_lshlrev_b32_e32 v150, 16, v188
	v_and_b32_e32 v151, 0xffff0000, v188
	v_lshlrev_b32_e32 v152, 16, v189
	v_and_b32_e32 v153, 0xffff0000, v189
	v_pk_mul_f32 v[146:147], v[146:147], s[100:101] op_sel_hi:[1,0]
	v_pk_mul_f32 v[148:149], v[148:149], s[100:101] op_sel_hi:[1,0]
	v_pk_mul_f32 v[150:151], v[150:151], s[100:101] op_sel_hi:[1,0]
	v_pk_mul_f32 v[152:153], v[152:153], s[100:101] op_sel_hi:[1,0]
	v_exp_f32_e32 v146, v146
	v_exp_f32_e32 v147, v147
	v_exp_f32_e32 v148, v148
	v_exp_f32_e32 v149, v149
	v_exp_f32_e32 v150, v150
	v_exp_f32_e32 v151, v151
	v_exp_f32_e32 v152, v152
	v_exp_f32_e32 v153, v153
	v_pk_add_f32 v[146:147], v[146:147], 1.0 op_sel_hi:[1,0]
	v_pk_add_f32 v[148:149], v[148:149], 1.0 op_sel_hi:[1,0]
	v_pk_add_f32 v[150:151], v[150:151], 1.0 op_sel_hi:[1,0]
	v_pk_add_f32 v[152:153], v[152:153], 1.0 op_sel_hi:[1,0]
	v_rcp_f32_e32 v146, v146
	v_rcp_f32_e32 v147, v147
	v_rcp_f32_e32 v148, v148
	v_rcp_f32_e32 v149, v149
	v_rcp_f32_e32 v150, v150
	v_rcp_f32_e32 v151, v151
	v_rcp_f32_e32 v152, v152
	v_rcp_f32_e32 v153, v153
	v_lshlrev_b32_e32 v162, 16, v190
	v_and_b32_e32 v163, 0xffff0000, v190
	v_lshlrev_b32_e32 v164, 16, v191
	v_and_b32_e32 v165, 0xffff0000, v191
	v_lshlrev_b32_e32 v166, 16, v192
	v_and_b32_e32 v167, 0xffff0000, v192
	v_lshlrev_b32_e32 v168, 16, v193
	v_and_b32_e32 v169, 0xffff0000, v193
	v_pk_fma_f32 v[162:163], v[30:31], v[146:147], v[162:163]
	v_pk_fma_f32 v[164:165], v[32:33], v[148:149], v[164:165]
	v_pk_fma_f32 v[166:167], v[26:27], v[150:151], v[166:167]
	v_pk_fma_f32 v[168:169], v[28:29], v[152:153], v[168:169]
	v_cvt_pk_bf16_f32 v162, v162, v163
	v_cvt_pk_bf16_f32 v163, v164, v165
	v_cvt_pk_bf16_f32 v164, v166, v167
	v_cvt_pk_bf16_f32 v165, v168, v169
	v_add_u32_e32 v132, 0x50000, v130
	global_store_dwordx4 v132, v[162:165], s[8:9] sc1
	s_waitcnt vmcnt(8)
	v_lshlrev_b32_e32 v146, 16, v194
	v_and_b32_e32 v147, 0xffff0000, v194
	v_lshlrev_b32_e32 v148, 16, v195
	v_and_b32_e32 v149, 0xffff0000, v195
	v_lshlrev_b32_e32 v150, 16, v196
	v_and_b32_e32 v151, 0xffff0000, v196
	v_lshlrev_b32_e32 v152, 16, v197
	v_and_b32_e32 v153, 0xffff0000, v197
	v_pk_mul_f32 v[146:147], v[146:147], s[100:101] op_sel_hi:[1,0]
	v_pk_mul_f32 v[148:149], v[148:149], s[100:101] op_sel_hi:[1,0]
	v_pk_mul_f32 v[150:151], v[150:151], s[100:101] op_sel_hi:[1,0]
	v_pk_mul_f32 v[152:153], v[152:153], s[100:101] op_sel_hi:[1,0]
	v_exp_f32_e32 v146, v146
	v_exp_f32_e32 v147, v147
	v_exp_f32_e32 v148, v148
	v_exp_f32_e32 v149, v149
	v_exp_f32_e32 v150, v150
	v_exp_f32_e32 v151, v151
	v_exp_f32_e32 v152, v152
	v_exp_f32_e32 v153, v153
	v_pk_add_f32 v[146:147], v[146:147], 1.0 op_sel_hi:[1,0]
	v_pk_add_f32 v[148:149], v[148:149], 1.0 op_sel_hi:[1,0]
	v_pk_add_f32 v[150:151], v[150:151], 1.0 op_sel_hi:[1,0]
	v_pk_add_f32 v[152:153], v[152:153], 1.0 op_sel_hi:[1,0]
	v_rcp_f32_e32 v146, v146
	v_rcp_f32_e32 v147, v147
	v_rcp_f32_e32 v148, v148
	v_rcp_f32_e32 v149, v149
	v_rcp_f32_e32 v150, v150
	v_rcp_f32_e32 v151, v151
	v_rcp_f32_e32 v152, v152
	v_rcp_f32_e32 v153, v153
	v_lshlrev_b32_e32 v162, 16, v198
	v_and_b32_e32 v163, 0xffff0000, v198
	v_lshlrev_b32_e32 v164, 16, v199
	v_and_b32_e32 v165, 0xffff0000, v199
	v_lshlrev_b32_e32 v166, 16, v200
	v_and_b32_e32 v167, 0xffff0000, v200
	v_lshlrev_b32_e32 v168, 16, v201
	v_and_b32_e32 v169, 0xffff0000, v201
	v_pk_fma_f32 v[162:163], v[22:23], v[146:147], v[162:163]
	v_pk_fma_f32 v[164:165], v[24:25], v[148:149], v[164:165]
	v_pk_fma_f32 v[166:167], v[18:19], v[150:151], v[166:167]
	v_pk_fma_f32 v[168:169], v[20:21], v[152:153], v[168:169]
	v_cvt_pk_bf16_f32 v162, v162, v163
	v_cvt_pk_bf16_f32 v163, v164, v165
	v_cvt_pk_bf16_f32 v164, v166, v167
	v_cvt_pk_bf16_f32 v165, v168, v169
	v_add_u32_e32 v132, 0x50000, v130
	global_store_dwordx4 v132, v[162:165], s[8:9] offset:256 sc1
	s_waitcnt vmcnt(6)
; __device__ __forceinline__ unsigned cvt_pk_bf16(float lo, float hi) { unsigned r; asm volatile("v_cvt_pk_bf16_f32 %0, %1, %2" : "=v"(r) : "v"(lo), "v"(hi)); return r; }
;     __device__ __forceinline__ void operator()(const f32x4 (&acc)[2][2][4][2], const Unit& u, int wr, int wc, int fr, int fq) const {
;     ...
;             for (int m = 0; m < 4; ++m) { const size_t ro = (size_t)(row0 + ai * HALF + m * 16) * ldc + col0;
; #pragma unroll
;                 for (int bj = 0; bj < 2; ++bj) { const f32x4 v0 = acc[ai][bj][m][0], v1 = acc[ai][bj][m][1];
;                     const u32x4 gw = *(const u32x4*)(G + ro + bj * HALF);
;                     float r[8]; const float a[8] = {v0[0], v0[1], v0[2], v0[3], v1[0], v1[1], v1[2], v1[3]};
; #pragma unroll
;                     for (int i = 0; i < 4; ++i) { const unsigned w = gw[i]; const float g0 = __builtin_bit_cast(float, w << 16), g1 = __builtin_bit_cast(float, w & 0xffff0000u);
;                         if (MODE == 0) { r[2 * i] = a[2 * i] * __builtin_amdgcn_rcpf(1.0f + __builtin_amdgcn_exp2f(-1.4426950408889634f * g0)); r[2 * i + 1] = a[2 * i + 1] * __builtin_amdgcn_rcpf(1.0f + __builtin_amdgcn_exp2f(-1.4426950408889634f * g1)); }
;                         else { r[2 * i] = g0 * a[2 * i] * __builtin_amdgcn_rcpf(1.0f + __builtin_amdgcn_exp2f(-1.4426950408889634f * a[2 * i])); r[2 * i + 1] = g1 * a[2 * i + 1] * __builtin_amdgcn_rcpf(1.0f + __builtin_amdgcn_exp2f(-1.4426950408889634f * a[2 * i + 1])); } }
;                     if (Add) { const u32x4 aw = *(const u32x4*)(Add + ro + bj * HALF);
; #pragma unroll
;                         for (int i = 0; i < 4; ++i) { const unsigned w = aw[i]; r[2 * i] += __builtin_bit_cast(float, w << 16); r[2 * i + 1] += __builtin_bit_cast(float, w & 0xffff0000u); } }
;                     u32x4 w; w.x = cvt_pk_bf16(r[0], r[1]); w.y = cvt_pk_bf16(r[2], r[3]); w.z = cvt_pk_bf16(r[4], r[5]); w.w = cvt_pk_bf16(r[6], r[7]);
;                     *(u32x4*)(O + ro + bj * HALF) = w; } }
	v_lshlrev_b32_e32 v146, 16, v202
	v_and_b32_e32 v147, 0xffff0000, v202
	v_lshlrev_b32_e32 v148, 16, v203
	v_and_b32_e32 v149, 0xffff0000, v203
	v_lshlrev_b32_e32 v150, 16, v204
	v_and_b32_e32 v151, 0xffff0000, v204
	v_lshlrev_b32_e32 v152, 16, v205
	v_and_b32_e32 v153, 0xffff0000, v205
	v_pk_mul_f32 v[146:147], v[146:147], s[100:101] op_sel_hi:[1,0]
	v_pk_mul_f32 v[148:149], v[148:149], s[100:101] op_sel_hi:[1,0]
	v_pk_mul_f32 v[150:151], v[150:151], s[100:101] op_sel_hi:[1,0]
	v_pk_mul_f32 v[152:153], v[152:153], s[100:101] op_sel_hi:[1,0]
	v_exp_f32_e32 v146, v146
	v_exp_f32_e32 v147, v147
	v_exp_f32_e32 v148, v148
	v_exp_f32_e32 v149, v149
	v_exp_f32_e32 v150, v150
	v_exp_f32_e32 v151, v151
	v_exp_f32_e32 v152, v152
	v_exp_f32_e32 v153, v153
	v_pk_add_f32 v[146:147], v[146:147], 1.0 op_sel_hi:[1,0]
	v_pk_add_f32 v[148:149], v[148:149], 1.0 op_sel_hi:[1,0]
	v_pk_add_f32 v[150:151], v[150:151], 1.0 op_sel_hi:[1,0]
	v_pk_add_f32 v[152:153], v[152:153], 1.0 op_sel_hi:[1,0]
	v_rcp_f32_e32 v146, v146
	v_rcp_f32_e32 v147, v147
	v_rcp_f32_e32 v148, v148
	v_rcp_f32_e32 v149, v149
	v_rcp_f32_e32 v150, v150
	v_rcp_f32_e32 v151, v151
	v_rcp_f32_e32 v152, v152
	v_rcp_f32_e32 v153, v153
	v_lshlrev_b32_e32 v162, 16, v206
	v_and_b32_e32 v163, 0xffff0000, v206
	v_lshlrev_b32_e32 v164, 16, v207
	v_and_b32_e32 v165, 0xffff0000, v207
	v_lshlrev_b32_e32 v166, 16, v208
	v_and_b32_e32 v167, 0xffff0000, v208
	v_lshlrev_b32_e32 v168, 16, v209
	v_and_b32_e32 v169, 0xffff0000, v209
	v_pk_fma_f32 v[162:163], v[14:15], v[146:147], v[162:163]
	v_pk_fma_f32 v[164:165], v[16:17], v[148:149], v[164:165]
	v_pk_fma_f32 v[166:167], v[10:11], v[150:151], v[166:167]
	v_pk_fma_f32 v[168:169], v[12:13], v[152:153], v[168:169]
	v_cvt_pk_bf16_f32 v162, v162, v163
	v_cvt_pk_bf16_f32 v163, v164, v165
	v_cvt_pk_bf16_f32 v164, v166, v167
	v_cvt_pk_bf16_f32 v165, v168, v169
	v_add_u32_e32 v132, 0x58000, v130
	global_store_dwordx4 v132, v[162:165], s[8:9] sc1
	s_waitcnt vmcnt(4)
	v_lshlrev_b32_e32 v146, 16, v170
	v_and_b32_e32 v147, 0xffff0000, v170
	v_lshlrev_b32_e32 v148, 16, v171
	v_and_b32_e32 v149, 0xffff0000, v171
	v_lshlrev_b32_e32 v150, 16, v172
	v_and_b32_e32 v151, 0xffff0000, v172
	v_lshlrev_b32_e32 v152, 16, v173
	v_and_b32_e32 v153, 0xffff0000, v173
	v_pk_mul_f32 v[146:147], v[146:147], s[100:101] op_sel_hi:[1,0]
	v_pk_mul_f32 v[148:149], v[148:149], s[100:101] op_sel_hi:[1,0]
	v_pk_mul_f32 v[150:151], v[150:151], s[100:101] op_sel_hi:[1,0]
	v_pk_mul_f32 v[152:153], v[152:153], s[100:101] op_sel_hi:[1,0]
	v_exp_f32_e32 v146, v146
	v_exp_f32_e32 v147, v147
	v_exp_f32_e32 v148, v148
	v_exp_f32_e32 v149, v149
	v_exp_f32_e32 v150, v150
	v_exp_f32_e32 v151, v151
	v_exp_f32_e32 v152, v152
	v_exp_f32_e32 v153, v153
	v_pk_add_f32 v[146:147], v[146:147], 1.0 op_sel_hi:[1,0]
	v_pk_add_f32 v[148:149], v[148:149], 1.0 op_sel_hi:[1,0]
	v_pk_add_f32 v[150:151], v[150:151], 1.0 op_sel_hi:[1,0]
	v_pk_add_f32 v[152:153], v[152:153], 1.0 op_sel_hi:[1,0]
	v_rcp_f32_e32 v146, v146
	v_rcp_f32_e32 v147, v147
	v_rcp_f32_e32 v148, v148
	v_rcp_f32_e32 v149, v149
	v_rcp_f32_e32 v150, v150
	v_rcp_f32_e32 v151, v151
	v_rcp_f32_e32 v152, v152
	v_rcp_f32_e32 v153, v153
	v_lshlrev_b32_e32 v162, 16, v174
	v_and_b32_e32 v163, 0xffff0000, v174
	v_lshlrev_b32_e32 v164, 16, v175
	v_and_b32_e32 v165, 0xffff0000, v175
	v_lshlrev_b32_e32 v166, 16, v176
	v_and_b32_e32 v167, 0xffff0000, v176
	v_lshlrev_b32_e32 v168, 16, v177
	v_and_b32_e32 v169, 0xffff0000, v177
	v_pk_fma_f32 v[162:163], v[6:7], v[146:147], v[162:163]
	v_pk_fma_f32 v[164:165], v[8:9], v[148:149], v[164:165]
	v_pk_fma_f32 v[166:167], v[2:3], v[150:151], v[166:167]
	v_pk_fma_f32 v[168:169], v[4:5], v[152:153], v[168:169]
	v_cvt_pk_bf16_f32 v162, v162, v163
	v_cvt_pk_bf16_f32 v163, v164, v165
	v_cvt_pk_bf16_f32 v164, v166, v167
	v_cvt_pk_bf16_f32 v165, v168, v169
	v_add_u32_e32 v132, 0x58000, v130
	global_store_dwordx4 v132, v[162:165], s[8:9] offset:256 sc1
	s_and_b64 vcc, exec, s[38:39]
	s_mov_b64 s[38:39], -1
	s_cbranch_vccnz .LBB0_882
	s_branch .LBB0_892

; __device__ __forceinline__ unsigned xb_ld(unsigned* p)              { return __hip_atomic_load(p, __ATOMIC_RELAXED, __HIP_MEMORY_SCOPE_AGENT); }
; __device__ __forceinline__ unsigned xb_add(unsigned* p, unsigned v) { return __hip_atomic_fetch_add(p, v, __ATOMIC_RELAXED, __HIP_MEMORY_SCOPE_AGENT); }
; #define XB_SPIN(cond, bar) do { unsigned _sp = 0; while (cond) { __builtin_amdgcn_s_sleep(1); \
;     if ((++_sp & 255u) == 0u) { if (xb_ld(&(bar)[XB_TMO])) break; if (_sp > XB_SPIN_CAP) { atomicAdd(&(bar)[XB_TMO], 1u); break; } } } } while (0)
; __device__ __forceinline__ void xcd_barrier(const XcdBarrier& b) {
;     asm volatile("s_waitcnt vmcnt(0)" ::: "memory");
;     __syncthreads();
;     if (threadIdx.x == 0) {
;         unsigned* bar = b.bar;
;         __builtin_amdgcn_s_waitcnt(0);
;         unsigned nloc = b.st[0], nx = b.st[1];
;         if (nloc == 0u) { xcd_barrier_complete(bar, b.x, nloc, nx); b.st[0] = nloc; b.st[1] = nx; }
;         const unsigned old = xb_add(&bar[XB_XSUB(b.x)], 1u);
;         const unsigned gen = old / nloc;
;         if (old + 1u == (gen + 1u) * nloc) {
;             __builtin_amdgcn_fence(__ATOMIC_RELEASE, "agent");
;             asm volatile("s_waitcnt vmcnt(0)" ::: "memory");
;             const unsigned og = xb_add(&bar[XB_TOP], 1u);
;             const unsigned tg = og / nx;
;             if (og + 1u == (tg + 1u) * nx) xb_add(&bar[XB_TOPGEN], 1u);
;             else XB_SPIN(xb_ld(&bar[XB_TOPGEN]) == tg, bar);
;             __builtin_amdgcn_fence(__ATOMIC_ACQUIRE, "agent");
;             xb_add(&bar[XB_XGEN(b.x)], 1u);
;             asm volatile("s_waitcnt vmcnt(0)" ::: "memory");
;         } else {
;             XB_SPIN(xb_ld(&bar[XB_XGEN(b.x)]) == gen, bar);
;             __builtin_amdgcn_fence(__ATOMIC_ACQUIRE, "agent");
;             asm volatile("s_waitcnt vmcnt(0)" ::: "memory");
;         }
;     }
;     __syncthreads();
; }
.LBB0_895:
	s_cmp_gt_i32 s87, 11
	s_cselect_b64 s[2:3], -1, 0
	s_and_b64 s[0:1], s[0:1], s[2:3]
	s_andn2_b64 vcc, exec, s[0:1]
	s_cbranch_vccnz .LBB0_949
	s_waitcnt vmcnt(0)
	s_waitcnt vmcnt(0) lgkmcnt(0)
	s_barrier
	s_and_saveexec_b64 s[0:1], s[88:89]
	s_cbranch_execz .LBB0_948
	v_readlane_b32 s4, v250, 6
	v_readlane_b32 s5, v250, 7
	v_readlane_b32 s6, v250, 28
	v_mov_b32_e32 v2, 0
	v_mov_b32_e32 v3, 1
	s_lshr_b32 s6, s6, 3
	s_and_b32 s7, s6, 7
	s_bfe_u32 s6, s6, 0x30003
	s_lshl_b32 s7, s7, 3
	s_add_i32 s6, s6, s7
	s_lshl_b32 s8, s6, 1
	s_and_b32 s8, s8, 63
	s_lshl_b32 s6, s6, 8
	s_lshl_b32 s8, s8, 8
	s_add_u32 s4, s4, 0x4c080
	s_addc_u32 s5, s5, 0
	s_add_u32 s8, s4, s8
	s_addc_u32 s9, s5, 0
	s_add_u32 s4, s4, s6
	s_addc_u32 s5, s5, 0
	s_mov_b32 s7, 0
	global_atomic_add v2, v3, s[4:5]
.Lpb10_poll:
	global_load_dword v4, v2, s[4:5] sc1
	global_load_dword v5, v2, s[8:9] sc1
	global_load_dword v6, v2, s[8:9] offset:256 sc1
	s_add_i32 s7, s7, 1
	s_waitcnt vmcnt(0)
	v_min_u32_e32 v4, v4, v5
	v_min_u32_e32 v4, v4, v6
	s_nop 0
	v_readfirstlane_b32 s6, v4
	s_nop 0
	s_nop 0
	s_cmp_ge_u32 s6, 4
	s_cbranch_scc1 .Lpb10_done
	s_cmp_ge_u32 s7, 0x400000
	s_cbranch_scc1 .Lpb10_done
	s_sleep 1
	s_branch .Lpb10_poll
